# v42 + one static s_setprio 1 for waves 4-7 at each GEMM loop entry (reset at exit), no per-segment toggles
# baseline (speedup 1.0000x reference)
.LBB0_37:
	s_add_i32 s9, s43, -2
	s_add_u32 s50, s18, 0x100
	s_addc_u32 s51, s19, 0
	s_mov_b32 s20, 0
	v_readfirstlane_b32 vcc_lo, v252
	s_nop 0
	s_cmpk_ge_u32 vcc_lo, 0x100
	s_cbranch_scc0 .Lsprio0
	s_setprio 1
.Lsprio0:
.LBB0_38:
	s_add_i32 s52, s20, 2
	s_add_u32 s18, s16, 0x100
	s_addc_u32 s19, s17, 0
	s_add_i32 s53, 0, 0x10000
	s_cmp_eq_u32 s9, s20
	s_cselect_b32 s23, s1, s19
	s_cselect_b32 s22, s0, s18
	s_cselect_b32 s21, s11, s51
	s_cselect_b32 s20, s10, s50
	s_add_i32 s54, 0, 0x14000
	v_add_u32_e32 v154, s53, v168
	v_add_u32_e32 v166, s54, v168
	ds_read_b128 v[142:145], v154
	ds_read_b128 v[146:149], v154 offset:1024
	ds_read_b128 v[150:153], v154 offset:2048
	ds_read_b128 v[154:157], v154 offset:3072
	ds_read_b128 v[158:161], v166
	ds_read_b128 v[162:165], v166 offset:1024
	ds_read_b128 v[172:175], v166 offset:2048
	ds_read_b128 v[176:179], v166 offset:3072
	v_lshl_add_u64 v[166:167], s[16:17], 0, v[138:139]
	s_add_i32 m0, s25, 0xc000
	ds_read_b128 v[180:183], v170
	ds_read_b128 v[184:187], v170 offset:1024
	ds_read_b128 v[188:191], v170 offset:2048
	ds_read_b128 v[192:195], v170 offset:3072
	ds_read_b128 v[196:199], v170 offset:4096
	ds_read_b128 v[200:203], v170 offset:5120
	ds_read_b128 v[204:207], v170 offset:6144
	ds_read_b128 v[208:211], v170 offset:7168
	global_load_lds_dwordx4 v[166:167], off
	v_lshl_add_u64 v[166:167], s[16:17], 0, v[140:141]
	s_add_i32 m0, s25, 0xe000
	s_nop 0
	global_load_lds_dwordx4 v[166:167], off
	s_waitcnt vmcnt(8)
	s_waitcnt lgkmcnt(0)
	s_barrier
	v_mfma_f32_16x16x32_bf16 v[130:133], v[142:145], v[180:183], v[130:133]
	v_mfma_f32_16x16x32_bf16 v[126:129], v[150:153], v[180:183], v[126:129]
	v_mfma_f32_16x16x32_bf16 v[122:125], v[142:145], v[188:191], v[122:125]
	v_mfma_f32_16x16x32_bf16 v[118:121], v[150:153], v[188:191], v[118:121]
	v_mfma_f32_16x16x32_bf16 v[114:117], v[142:145], v[196:199], v[114:117]
	v_mfma_f32_16x16x32_bf16 v[110:113], v[150:153], v[196:199], v[110:113]
	v_mfma_f32_16x16x32_bf16 v[106:109], v[142:145], v[204:207], v[106:109]
	v_mfma_f32_16x16x32_bf16 v[102:105], v[150:153], v[204:207], v[102:105]
	v_mfma_f32_16x16x32_bf16 v[130:133], v[146:149], v[184:187], v[130:133]
	v_mfma_f32_16x16x32_bf16 v[126:129], v[154:157], v[184:187], v[126:129]
	v_mfma_f32_16x16x32_bf16 v[122:125], v[146:149], v[192:195], v[122:125]
	v_mfma_f32_16x16x32_bf16 v[118:121], v[154:157], v[192:195], v[118:121]
	v_mfma_f32_16x16x32_bf16 v[114:117], v[146:149], v[200:203], v[114:117]
	v_mfma_f32_16x16x32_bf16 v[110:113], v[154:157], v[200:203], v[110:113]
	v_mfma_f32_16x16x32_bf16 v[106:109], v[146:149], v[208:211], v[106:109]
	v_mfma_f32_16x16x32_bf16 v[102:105], v[154:157], v[208:211], v[102:105]
	v_mfma_f32_16x16x32_bf16 v[98:101], v[158:161], v[180:183], v[98:101]
	v_mfma_f32_16x16x32_bf16 v[94:97], v[172:175], v[180:183], v[94:97]
	v_mfma_f32_16x16x32_bf16 v[90:93], v[158:161], v[188:191], v[90:93]
	v_mfma_f32_16x16x32_bf16 v[86:89], v[172:175], v[188:191], v[86:89]
	v_mfma_f32_16x16x32_bf16 v[82:85], v[158:161], v[196:199], v[82:85]
	v_mfma_f32_16x16x32_bf16 v[78:81], v[172:175], v[196:199], v[78:81]
	v_mfma_f32_16x16x32_bf16 v[74:77], v[158:161], v[204:207], v[74:77]
	v_mfma_f32_16x16x32_bf16 v[70:73], v[172:175], v[204:207], v[70:73]
	v_mfma_f32_16x16x32_bf16 v[98:101], v[162:165], v[184:187], v[98:101]
	v_mfma_f32_16x16x32_bf16 v[94:97], v[176:179], v[184:187], v[94:97]
	v_mfma_f32_16x16x32_bf16 v[90:93], v[162:165], v[192:195], v[90:93]
	v_mfma_f32_16x16x32_bf16 v[86:89], v[176:179], v[192:195], v[86:89]
	v_mfma_f32_16x16x32_bf16 v[82:85], v[162:165], v[200:203], v[82:85]
	v_mfma_f32_16x16x32_bf16 v[78:81], v[176:179], v[200:203], v[78:81]
	v_mfma_f32_16x16x32_bf16 v[74:77], v[162:165], v[208:211], v[74:77]
	v_mfma_f32_16x16x32_bf16 v[70:73], v[176:179], v[208:211], v[70:73]
	s_barrier
	s_add_i32 s16, s53, s24
	v_lshl_add_u64 v[166:167], s[20:21], 0, v[0:1]
	s_mov_b32 m0, s16
	ds_read_b128 v[180:183], v170 offset:16384
	ds_read_b128 v[184:187], v170 offset:17408
	ds_read_b128 v[188:191], v170 offset:18432
	ds_read_b128 v[192:195], v170 offset:19456
	ds_read_b128 v[196:199], v170 offset:20480
	ds_read_b128 v[200:203], v170 offset:21504
	ds_read_b128 v[204:207], v170 offset:22528
	ds_read_b128 v[208:211], v170 offset:23552
	global_load_lds_dwordx4 v[166:167], off
	s_add_i32 m0, s16, 0x2000
	s_add_u32 s16, s20, 0xc0000
	v_lshl_add_u64 v[212:213], s[20:21], 0, v[136:137]
	s_addc_u32 s17, s21, 0
	s_add_i32 s53, s54, s24
	global_load_lds_dwordx4 v[212:213], off
	v_lshl_add_u64 v[214:215], s[16:17], 0, v[0:1]
	s_mov_b32 m0, s53
	v_lshl_add_u64 v[216:217], s[22:23], 0, v[134:135]
	global_load_lds_dwordx4 v[214:215], off
	v_lshl_add_u64 v[214:215], s[16:17], 0, v[136:137]
	s_add_i32 m0, s53, 0x2000
	s_nop 0
	global_load_lds_dwordx4 v[214:215], off
	v_lshl_add_u64 v[214:215], s[22:23], 0, v[14:15]
	s_mov_b32 m0, s25
	s_nop 0
	global_load_lds_dwordx4 v[214:215], off
	s_mov_b32 m0, s26
	s_nop 0
	global_load_lds_dwordx4 v[216:217], off
	s_waitcnt vmcnt(8)
	s_waitcnt lgkmcnt(0)
	s_barrier
	v_mfma_f32_16x16x32_bf16 v[66:69], v[142:145], v[180:183], v[66:69]
	v_mfma_f32_16x16x32_bf16 v[62:65], v[150:153], v[180:183], v[62:65]
	v_mfma_f32_16x16x32_bf16 v[58:61], v[142:145], v[188:191], v[58:61]
	v_mfma_f32_16x16x32_bf16 v[54:57], v[150:153], v[188:191], v[54:57]
	v_mfma_f32_16x16x32_bf16 v[50:53], v[142:145], v[196:199], v[50:53]
	v_mfma_f32_16x16x32_bf16 v[46:49], v[150:153], v[196:199], v[46:49]
	v_mfma_f32_16x16x32_bf16 v[42:45], v[142:145], v[204:207], v[42:45]
	v_mfma_f32_16x16x32_bf16 v[38:41], v[150:153], v[204:207], v[38:41]
	v_mfma_f32_16x16x32_bf16 v[66:69], v[146:149], v[184:187], v[66:69]
	v_mfma_f32_16x16x32_bf16 v[62:65], v[154:157], v[184:187], v[62:65]
	v_mfma_f32_16x16x32_bf16 v[58:61], v[146:149], v[192:195], v[58:61]
	v_mfma_f32_16x16x32_bf16 v[54:57], v[154:157], v[192:195], v[54:57]
	v_mfma_f32_16x16x32_bf16 v[50:53], v[146:149], v[200:203], v[50:53]
	v_mfma_f32_16x16x32_bf16 v[46:49], v[154:157], v[200:203], v[46:49]
	v_mfma_f32_16x16x32_bf16 v[42:45], v[146:149], v[208:211], v[42:45]
	v_mfma_f32_16x16x32_bf16 v[38:41], v[154:157], v[208:211], v[38:41]
	v_mfma_f32_16x16x32_bf16 v[34:37], v[158:161], v[180:183], v[34:37]
	v_mfma_f32_16x16x32_bf16 v[30:33], v[172:175], v[180:183], v[30:33]
	v_mfma_f32_16x16x32_bf16 v[26:29], v[158:161], v[188:191], v[26:29]
	v_mfma_f32_16x16x32_bf16 v[22:25], v[172:175], v[188:191], v[22:25]
	v_mfma_f32_16x16x32_bf16 v[18:21], v[158:161], v[196:199], v[18:21]
	v_mfma_f32_16x16x32_bf16 v[10:13], v[172:175], v[196:199], v[10:13]
	v_mfma_f32_16x16x32_bf16 v[6:9], v[158:161], v[204:207], v[6:9]
	v_mfma_f32_16x16x32_bf16 v[2:5], v[172:175], v[204:207], v[2:5]
	v_mfma_f32_16x16x32_bf16 v[34:37], v[162:165], v[184:187], v[34:37]
	v_mfma_f32_16x16x32_bf16 v[30:33], v[176:179], v[184:187], v[30:33]
	v_mfma_f32_16x16x32_bf16 v[26:29], v[162:165], v[192:195], v[26:29]
	v_mfma_f32_16x16x32_bf16 v[22:25], v[176:179], v[192:195], v[22:25]
	v_mfma_f32_16x16x32_bf16 v[18:21], v[162:165], v[200:203], v[18:21]
	v_mfma_f32_16x16x32_bf16 v[10:13], v[176:179], v[200:203], v[10:13]
	v_mfma_f32_16x16x32_bf16 v[6:9], v[162:165], v[208:211], v[6:9]
	v_mfma_f32_16x16x32_bf16 v[2:5], v[176:179], v[208:211], v[2:5]
	s_barrier
	s_add_i32 s53, 0, 0x18000
	s_add_i32 s54, 0, 0x1c000
	v_add_u32_e32 v154, s53, v168
	v_add_u32_e32 v171, s54, v168
	ds_read_b128 v[142:145], v154
	ds_read_b128 v[146:149], v154 offset:1024
	ds_read_b128 v[150:153], v154 offset:2048
	ds_read_b128 v[154:157], v154 offset:3072
	ds_read_b128 v[158:161], v171
	ds_read_b128 v[162:165], v171 offset:1024
	ds_read_b128 v[172:175], v171 offset:2048
	ds_read_b128 v[176:179], v171 offset:3072
	s_add_u32 s16, s22, 0xc0000
	s_addc_u32 s17, s23, 0
	s_mov_b32 m0, s27
	v_lshl_add_u64 v[218:219], s[16:17], 0, v[14:15]
	ds_read_b128 v[180:183], v170 offset:32768
	ds_read_b128 v[184:187], v170 offset:33792
	ds_read_b128 v[188:191], v170 offset:34816
	ds_read_b128 v[192:195], v170 offset:35840
	ds_read_b128 v[196:199], v170 offset:36864
	ds_read_b128 v[200:203], v170 offset:37888
	ds_read_b128 v[204:207], v170 offset:38912
	ds_read_b128 v[208:211], v170 offset:39936
	global_load_lds_dwordx4 v[218:219], off
	v_lshl_add_u64 v[218:219], s[16:17], 0, v[134:135]
	s_mov_b32 m0, s33
	s_nop 0
	global_load_lds_dwordx4 v[218:219], off
	s_waitcnt vmcnt(8)
	s_waitcnt lgkmcnt(0)
	s_barrier
	v_mfma_f32_16x16x32_bf16 v[130:133], v[142:145], v[180:183], v[130:133]
	v_mfma_f32_16x16x32_bf16 v[126:129], v[150:153], v[180:183], v[126:129]
	v_mfma_f32_16x16x32_bf16 v[122:125], v[142:145], v[188:191], v[122:125]
	v_mfma_f32_16x16x32_bf16 v[118:121], v[150:153], v[188:191], v[118:121]
	v_mfma_f32_16x16x32_bf16 v[114:117], v[142:145], v[196:199], v[114:117]
	v_mfma_f32_16x16x32_bf16 v[110:113], v[150:153], v[196:199], v[110:113]
	v_mfma_f32_16x16x32_bf16 v[106:109], v[142:145], v[204:207], v[106:109]
	v_mfma_f32_16x16x32_bf16 v[102:105], v[150:153], v[204:207], v[102:105]
	v_mfma_f32_16x16x32_bf16 v[130:133], v[146:149], v[184:187], v[130:133]
	v_mfma_f32_16x16x32_bf16 v[126:129], v[154:157], v[184:187], v[126:129]
	v_mfma_f32_16x16x32_bf16 v[122:125], v[146:149], v[192:195], v[122:125]
	v_mfma_f32_16x16x32_bf16 v[118:121], v[154:157], v[192:195], v[118:121]
	v_mfma_f32_16x16x32_bf16 v[114:117], v[146:149], v[200:203], v[114:117]
	v_mfma_f32_16x16x32_bf16 v[110:113], v[154:157], v[200:203], v[110:113]
	v_mfma_f32_16x16x32_bf16 v[106:109], v[146:149], v[208:211], v[106:109]
	v_mfma_f32_16x16x32_bf16 v[102:105], v[154:157], v[208:211], v[102:105]
	v_mfma_f32_16x16x32_bf16 v[98:101], v[158:161], v[180:183], v[98:101]
	v_mfma_f32_16x16x32_bf16 v[94:97], v[172:175], v[180:183], v[94:97]
	v_mfma_f32_16x16x32_bf16 v[90:93], v[158:161], v[188:191], v[90:93]
	v_mfma_f32_16x16x32_bf16 v[86:89], v[172:175], v[188:191], v[86:89]
	v_mfma_f32_16x16x32_bf16 v[82:85], v[158:161], v[196:199], v[82:85]
	v_mfma_f32_16x16x32_bf16 v[78:81], v[172:175], v[196:199], v[78:81]
	v_mfma_f32_16x16x32_bf16 v[74:77], v[158:161], v[204:207], v[74:77]
	v_mfma_f32_16x16x32_bf16 v[70:73], v[172:175], v[204:207], v[70:73]
	v_mfma_f32_16x16x32_bf16 v[98:101], v[162:165], v[184:187], v[98:101]
	v_mfma_f32_16x16x32_bf16 v[94:97], v[176:179], v[184:187], v[94:97]
	v_mfma_f32_16x16x32_bf16 v[90:93], v[162:165], v[192:195], v[90:93]
	v_mfma_f32_16x16x32_bf16 v[86:89], v[176:179], v[192:195], v[86:89]
	v_mfma_f32_16x16x32_bf16 v[82:85], v[162:165], v[200:203], v[82:85]
	v_mfma_f32_16x16x32_bf16 v[78:81], v[176:179], v[200:203], v[78:81]
	v_mfma_f32_16x16x32_bf16 v[74:77], v[162:165], v[208:211], v[74:77]
	v_mfma_f32_16x16x32_bf16 v[70:73], v[176:179], v[208:211], v[70:73]
	s_barrier
	s_add_i32 s16, s53, s24
	v_lshl_add_u64 v[166:167], v[166:167], 0, s[36:37]
	s_mov_b32 m0, s16
	ds_read_b128 v[180:183], v170 offset:49152
	ds_read_b128 v[184:187], v170 offset:50176
	ds_read_b128 v[188:191], v170 offset:51200
	ds_read_b128 v[192:195], v170 offset:52224
	ds_read_b128 v[196:199], v170 offset:53248
	ds_read_b128 v[200:203], v170 offset:54272
	ds_read_b128 v[204:207], v170 offset:55296
	ds_read_b128 v[208:211], v170 offset:56320
	global_load_lds_dwordx4 v[166:167], off
	s_add_i32 m0, s16, 0x2000
	s_add_u32 s16, s20, 0xc0080
	v_lshl_add_u64 v[166:167], v[212:213], 0, s[36:37]
	s_addc_u32 s17, s21, 0
	s_add_i32 s20, s54, s24
	global_load_lds_dwordx4 v[166:167], off
	v_lshl_add_u64 v[166:167], s[16:17], 0, v[0:1]
	s_mov_b32 m0, s20
	s_nop 0
	global_load_lds_dwordx4 v[166:167], off
	v_lshl_add_u64 v[166:167], s[16:17], 0, v[136:137]
	s_add_i32 m0, s20, 0x2000
	s_nop 0
	global_load_lds_dwordx4 v[166:167], off
	v_lshl_add_u64 v[166:167], v[214:215], 0, s[36:37]
	s_mov_b32 m0, s45
	s_nop 0
	global_load_lds_dwordx4 v[166:167], off
	v_lshl_add_u64 v[166:167], v[216:217], 0, s[36:37]
	s_mov_b32 m0, s46
	s_nop 0
	global_load_lds_dwordx4 v[166:167], off
	s_waitcnt vmcnt(8)
	s_waitcnt lgkmcnt(0)
	s_barrier
	v_mfma_f32_16x16x32_bf16 v[66:69], v[142:145], v[180:183], v[66:69]
	v_mfma_f32_16x16x32_bf16 v[62:65], v[150:153], v[180:183], v[62:65]
	v_mfma_f32_16x16x32_bf16 v[58:61], v[142:145], v[188:191], v[58:61]
	v_mfma_f32_16x16x32_bf16 v[54:57], v[150:153], v[188:191], v[54:57]
	v_mfma_f32_16x16x32_bf16 v[50:53], v[142:145], v[196:199], v[50:53]
	v_mfma_f32_16x16x32_bf16 v[46:49], v[150:153], v[196:199], v[46:49]
	v_mfma_f32_16x16x32_bf16 v[42:45], v[142:145], v[204:207], v[42:45]
	v_mfma_f32_16x16x32_bf16 v[38:41], v[150:153], v[204:207], v[38:41]
	v_mfma_f32_16x16x32_bf16 v[66:69], v[146:149], v[184:187], v[66:69]
	v_mfma_f32_16x16x32_bf16 v[62:65], v[154:157], v[184:187], v[62:65]
	v_mfma_f32_16x16x32_bf16 v[58:61], v[146:149], v[192:195], v[58:61]
	v_mfma_f32_16x16x32_bf16 v[54:57], v[154:157], v[192:195], v[54:57]
	v_mfma_f32_16x16x32_bf16 v[50:53], v[146:149], v[200:203], v[50:53]
	v_mfma_f32_16x16x32_bf16 v[46:49], v[154:157], v[200:203], v[46:49]
	v_mfma_f32_16x16x32_bf16 v[42:45], v[146:149], v[208:211], v[42:45]
	v_mfma_f32_16x16x32_bf16 v[38:41], v[154:157], v[208:211], v[38:41]
	v_mfma_f32_16x16x32_bf16 v[34:37], v[158:161], v[180:183], v[34:37]
	v_mfma_f32_16x16x32_bf16 v[30:33], v[172:175], v[180:183], v[30:33]
	v_mfma_f32_16x16x32_bf16 v[26:29], v[158:161], v[188:191], v[26:29]
	v_mfma_f32_16x16x32_bf16 v[22:25], v[172:175], v[188:191], v[22:25]
	v_mfma_f32_16x16x32_bf16 v[18:21], v[158:161], v[196:199], v[18:21]
	v_mfma_f32_16x16x32_bf16 v[10:13], v[172:175], v[196:199], v[10:13]
	v_mfma_f32_16x16x32_bf16 v[6:9], v[158:161], v[204:207], v[6:9]
	v_mfma_f32_16x16x32_bf16 v[2:5], v[172:175], v[204:207], v[2:5]
	v_mfma_f32_16x16x32_bf16 v[34:37], v[162:165], v[184:187], v[34:37]
	v_mfma_f32_16x16x32_bf16 v[30:33], v[176:179], v[184:187], v[30:33]
	v_mfma_f32_16x16x32_bf16 v[26:29], v[162:165], v[192:195], v[26:29]
	v_mfma_f32_16x16x32_bf16 v[22:25], v[176:179], v[192:195], v[22:25]
	v_mfma_f32_16x16x32_bf16 v[18:21], v[162:165], v[200:203], v[18:21]
	v_mfma_f32_16x16x32_bf16 v[10:13], v[176:179], v[200:203], v[10:13]
	v_mfma_f32_16x16x32_bf16 v[6:9], v[162:165], v[208:211], v[6:9]
	v_mfma_f32_16x16x32_bf16 v[2:5], v[176:179], v[208:211], v[2:5]
	s_barrier
	s_add_u32 s50, s50, 0x100
	s_addc_u32 s51, s51, 0
	s_cmp_ge_i32 s52, s43
	s_mov_b64 s[16:17], s[18:19]
	s_mov_b32 s20, s52
	s_cbranch_scc0 .LBB0_38
	s_setprio 0
	s_and_b64 vcc, exec, s[6:7]
	s_cbranch_vccz .LBB0_41
	s_barrier

.LBB0_163:
	s_ashr_i32 s9, s8, 31
	s_lshl_b64 s[4:5], s[8:9], 20
	s_add_u32 s16, s90, s4
	s_addc_u32 s17, s91, s5
	s_and_b64 s[4:5], s[44:45], exec
	s_cselect_b32 s9, s17, s19
	s_cselect_b32 s21, s16, s18
	s_ashr_i32 s1, s0, 31
	s_lshl_b64 s[4:5], s[0:1], 20
	s_add_u32 s4, s12, s4
	s_addc_u32 s5, s15, s5
	s_and_b64 s[46:47], s[44:45], exec
	s_cselect_b32 s1, s5, s25
	s_cselect_b32 s23, s4, s24
	s_add_u32 s18, s18, 0x80080
	s_addc_u32 s19, s19, 0
	s_add_u32 s29, s24, 0x100
	v_mov_b32_e32 v8, 0
	s_addc_u32 s50, s25, 0
	s_mov_b32 s51, -2
	v_mov_b32_e32 v9, v8
	s_waitcnt vmcnt(0)
	v_mov_b32_e32 v10, v8
	v_mov_b32_e32 v11, v8
	v_mov_b32_e32 v12, v8
	v_mov_b32_e32 v13, v8
	v_mov_b32_e32 v14, v8
	v_mov_b32_e32 v15, v8
	v_mov_b32_e32 v2, v8
	v_mov_b32_e32 v3, v8
	v_mov_b32_e32 v4, v8
	v_mov_b32_e32 v5, v8
	v_mov_b32_e32 v26, v8
	v_mov_b32_e32 v27, v8
	v_mov_b32_e32 v28, v8
	v_mov_b32_e32 v29, v8
	v_mov_b32_e32 v30, v8
	v_mov_b32_e32 v31, v8
	v_mov_b32_e32 v32, v8
	v_mov_b32_e32 v33, v8
	v_mov_b32_e32 v34, v8
	v_mov_b32_e32 v35, v8
	v_mov_b32_e32 v36, v8
	v_mov_b32_e32 v37, v8
	v_mov_b32_e32 v46, v8
	v_mov_b32_e32 v47, v8
	v_mov_b32_e32 v48, v8
	v_mov_b32_e32 v49, v8
	v_mov_b32_e32 v50, v8
	v_mov_b32_e32 v51, v8
	v_mov_b32_e32 v52, v8
	v_mov_b32_e32 v53, v8
	v_mov_b32_e32 v18, v8
	v_mov_b32_e32 v19, v8
	v_mov_b32_e32 v20, v8
	v_mov_b32_e32 v21, v8
	v_mov_b32_e32 v22, v8
	v_mov_b32_e32 v23, v8
	v_mov_b32_e32 v24, v8
	v_mov_b32_e32 v25, v8
	v_mov_b32_e32 v38, v8
	v_mov_b32_e32 v39, v8
	v_mov_b32_e32 v40, v8
	v_mov_b32_e32 v41, v8
	v_mov_b32_e32 v42, v8
	v_mov_b32_e32 v43, v8
	v_mov_b32_e32 v44, v8
	v_mov_b32_e32 v45, v8
	v_mov_b32_e32 v54, v8
	v_mov_b32_e32 v55, v8
	v_mov_b32_e32 v56, v8
	v_mov_b32_e32 v57, v8
	v_mov_b32_e32 v58, v8
	v_mov_b32_e32 v59, v8
	v_mov_b32_e32 v60, v8
	v_mov_b32_e32 v61, v8
	v_mov_b32_e32 v70, v8
	v_mov_b32_e32 v71, v8
	v_mov_b32_e32 v72, v8
	v_mov_b32_e32 v73, v8
	v_mov_b32_e32 v74, v8
	v_mov_b32_e32 v75, v8
	v_mov_b32_e32 v76, v8
	v_mov_b32_e32 v77, v8
	v_mov_b32_e32 v62, v8
	v_mov_b32_e32 v63, v8
	v_mov_b32_e32 v64, v8
	v_mov_b32_e32 v65, v8
	v_mov_b32_e32 v66, v8
	v_mov_b32_e32 v67, v8
	v_mov_b32_e32 v68, v8
	v_mov_b32_e32 v69, v8
	v_mov_b32_e32 v78, v8
	v_mov_b32_e32 v79, v8
	v_mov_b32_e32 v80, v8
	v_mov_b32_e32 v81, v8
	v_mov_b32_e32 v82, v8
	v_mov_b32_e32 v83, v8
	v_mov_b32_e32 v84, v8
	v_mov_b32_e32 v85, v8
	v_mov_b32_e32 v94, v8
	v_mov_b32_e32 v95, v8
	v_mov_b32_e32 v96, v8
	v_mov_b32_e32 v97, v8
	v_mov_b32_e32 v98, v8
	v_mov_b32_e32 v99, v8
	v_mov_b32_e32 v100, v8
	v_mov_b32_e32 v101, v8
	v_mov_b32_e32 v110, v8
	v_mov_b32_e32 v111, v8
	v_mov_b32_e32 v112, v8
	v_mov_b32_e32 v113, v8
	v_mov_b32_e32 v114, v8
	v_mov_b32_e32 v115, v8
	v_mov_b32_e32 v116, v8
	v_mov_b32_e32 v117, v8
	v_mov_b32_e32 v86, v8
	v_mov_b32_e32 v87, v8
	v_mov_b32_e32 v88, v8
	v_mov_b32_e32 v89, v8
	v_mov_b32_e32 v90, v8
	v_mov_b32_e32 v91, v8
	v_mov_b32_e32 v92, v8
	v_mov_b32_e32 v93, v8
	v_mov_b32_e32 v102, v8
	v_mov_b32_e32 v103, v8
	v_mov_b32_e32 v104, v8
	v_mov_b32_e32 v105, v8
	v_mov_b32_e32 v106, v8
	v_mov_b32_e32 v107, v8
	v_mov_b32_e32 v108, v8
	v_mov_b32_e32 v109, v8
	v_mov_b32_e32 v118, v8
	v_mov_b32_e32 v119, v8
	v_mov_b32_e32 v120, v8
	v_mov_b32_e32 v121, v8
	v_mov_b32_e32 v122, v8
	v_mov_b32_e32 v123, v8
	v_mov_b32_e32 v124, v8
	v_mov_b32_e32 v125, v8
	v_mov_b32_e32 v134, v8
	v_mov_b32_e32 v135, v8
	v_mov_b32_e32 v136, v8
	v_mov_b32_e32 v137, v8
	v_mov_b32_e32 v138, v8
	v_mov_b32_e32 v139, v8
	v_mov_b32_e32 v140, v8
	v_mov_b32_e32 v141, v8
	v_readfirstlane_b32 vcc_lo, v252
	s_nop 0
	s_cmpk_ge_u32 vcc_lo, 0x100
	s_cbranch_scc0 .Lsprio1
	s_setprio 1
.Lsprio1:
.LBB0_164:
	s_add_u32 s24, s18, 0xfff80080
	s_addc_u32 s25, s19, -1
	s_add_i32 s52, 0, 0x10000
	s_cmp_eq_u32 s51, 28
	s_cselect_b32 s47, s9, s25
	s_cselect_b32 s46, s21, s24
	v_add_u32_e32 v6, s52, v172
	s_cselect_b32 s25, s1, s50
	s_cselect_b32 s24, s23, s29
	s_add_i32 s54, 0, 0x14000
	ds_read_b128 v[126:129], v6
	ds_read_b128 v[130:133], v6 offset:1024
	ds_read_b128 v[142:145], v6 offset:2048
	ds_read_b128 v[146:149], v6 offset:3072
	v_add_u32_e32 v6, s54, v172
	ds_read_b128 v[166:169], v6
	ds_read_b128 v[204:207], v6 offset:1024
	ds_read_b128 v[208:211], v6 offset:2048
	ds_read_b128 v[216:219], v6 offset:3072
	v_lshl_add_u64 v[6:7], s[18:19], 0, v[162:163]
	s_add_i32 m0, s79, 0xc000
	ds_read_b128 v[220:223], v198
	ds_read_b128 v[224:227], v198 offset:1024
	ds_read_b128 v[228:231], v198 offset:2048
	ds_read_b128 v[232:235], v198 offset:3072
	ds_read_b128 v[236:239], v198 offset:4096
	ds_read_b128 v[240:243], v198 offset:5120
	ds_read_b128 v[244:247], v198 offset:6144
	ds_read_b128 v[248:251], v198 offset:7168
	global_load_lds_dwordx4 v[6:7], off
	v_lshl_add_u64 v[6:7], s[18:19], 0, v[164:165]
	s_add_i32 m0, s79, 0xe000
	s_nop 0
	global_load_lds_dwordx4 v[6:7], off
	s_waitcnt vmcnt(8)
	s_waitcnt lgkmcnt(0)
	s_barrier
	v_mfma_f32_16x16x32_bf16 v[138:141], v[126:129], v[220:223], v[138:141]
	v_mfma_f32_16x16x32_bf16 v[134:137], v[142:145], v[220:223], v[134:137]
	v_mfma_f32_16x16x32_bf16 v[122:125], v[126:129], v[228:231], v[122:125]
	v_mfma_f32_16x16x32_bf16 v[118:121], v[142:145], v[228:231], v[118:121]
	v_mfma_f32_16x16x32_bf16 v[106:109], v[126:129], v[236:239], v[106:109]
	v_mfma_f32_16x16x32_bf16 v[102:105], v[142:145], v[236:239], v[102:105]
	v_mfma_f32_16x16x32_bf16 v[90:93], v[126:129], v[244:247], v[90:93]
	v_mfma_f32_16x16x32_bf16 v[86:89], v[142:145], v[244:247], v[86:89]
	v_mfma_f32_16x16x32_bf16 v[138:141], v[130:133], v[224:227], v[138:141]
	v_mfma_f32_16x16x32_bf16 v[134:137], v[146:149], v[224:227], v[134:137]
	v_mfma_f32_16x16x32_bf16 v[122:125], v[130:133], v[232:235], v[122:125]
	v_mfma_f32_16x16x32_bf16 v[118:121], v[146:149], v[232:235], v[118:121]
	v_mfma_f32_16x16x32_bf16 v[106:109], v[130:133], v[240:243], v[106:109]
	v_mfma_f32_16x16x32_bf16 v[102:105], v[146:149], v[240:243], v[102:105]
	v_mfma_f32_16x16x32_bf16 v[90:93], v[130:133], v[248:251], v[90:93]
	v_mfma_f32_16x16x32_bf16 v[86:89], v[146:149], v[248:251], v[86:89]
	v_mfma_f32_16x16x32_bf16 v[114:117], v[166:169], v[220:223], v[114:117]
	v_mfma_f32_16x16x32_bf16 v[110:113], v[208:211], v[220:223], v[110:113]
	v_mfma_f32_16x16x32_bf16 v[98:101], v[166:169], v[228:231], v[98:101]
	v_mfma_f32_16x16x32_bf16 v[94:97], v[208:211], v[228:231], v[94:97]
	v_mfma_f32_16x16x32_bf16 v[82:85], v[166:169], v[236:239], v[82:85]
	v_mfma_f32_16x16x32_bf16 v[78:81], v[208:211], v[236:239], v[78:81]
	v_mfma_f32_16x16x32_bf16 v[66:69], v[166:169], v[244:247], v[66:69]
	v_mfma_f32_16x16x32_bf16 v[62:65], v[208:211], v[244:247], v[62:65]
	v_mfma_f32_16x16x32_bf16 v[114:117], v[204:207], v[224:227], v[114:117]
	v_mfma_f32_16x16x32_bf16 v[110:113], v[216:219], v[224:227], v[110:113]
	v_mfma_f32_16x16x32_bf16 v[98:101], v[204:207], v[232:235], v[98:101]
	v_mfma_f32_16x16x32_bf16 v[94:97], v[216:219], v[232:235], v[94:97]
	v_mfma_f32_16x16x32_bf16 v[82:85], v[204:207], v[240:243], v[82:85]
	v_mfma_f32_16x16x32_bf16 v[78:81], v[216:219], v[240:243], v[78:81]
	v_mfma_f32_16x16x32_bf16 v[66:69], v[204:207], v[248:251], v[66:69]
	v_mfma_f32_16x16x32_bf16 v[62:65], v[216:219], v[248:251], v[62:65]
	s_barrier
	s_add_i32 s52, s52, s33
	v_lshl_add_u64 v[170:171], s[24:25], 0, v[0:1]
	s_mov_b32 m0, s52
	ds_read_b128 v[220:223], v198 offset:16384
	ds_read_b128 v[224:227], v198 offset:17408
	ds_read_b128 v[228:231], v198 offset:18432
	ds_read_b128 v[232:235], v198 offset:19456
	ds_read_b128 v[236:239], v198 offset:20480
	ds_read_b128 v[240:243], v198 offset:21504
	ds_read_b128 v[244:247], v198 offset:22528
	ds_read_b128 v[248:251], v198 offset:23552
	global_load_lds_dwordx4 v[170:171], off
	s_add_i32 m0, s52, 0x2000
	s_add_u32 s52, s24, 0x80000
	v_lshl_add_u64 v[200:201], s[24:25], 0, v[154:155]
	s_addc_u32 s53, s25, 0
	s_add_i32 s54, s54, s33
	global_load_lds_dwordx4 v[200:201], off
	v_lshl_add_u64 v[6:7], s[52:53], 0, v[0:1]
	s_mov_b32 m0, s54
	v_lshl_add_u64 v[202:203], s[46:47], 0, v[150:151]
	global_load_lds_dwordx4 v[6:7], off
	v_lshl_add_u64 v[6:7], s[52:53], 0, v[154:155]
	s_add_i32 m0, s54, 0x2000
	v_lshl_add_u64 v[212:213], s[46:47], 0, v[152:153]
	global_load_lds_dwordx4 v[6:7], off
	s_mov_b32 m0, s79
	s_nop 0
	global_load_lds_dwordx4 v[202:203], off
	s_mov_b32 m0, s81
	s_nop 0
	global_load_lds_dwordx4 v[212:213], off
	s_waitcnt vmcnt(8)
	s_waitcnt lgkmcnt(0)
	s_barrier
	v_mfma_f32_16x16x32_bf16 v[74:77], v[126:129], v[220:223], v[74:77]
	v_mfma_f32_16x16x32_bf16 v[70:73], v[142:145], v[220:223], v[70:73]
	v_mfma_f32_16x16x32_bf16 v[58:61], v[126:129], v[228:231], v[58:61]
	v_mfma_f32_16x16x32_bf16 v[54:57], v[142:145], v[228:231], v[54:57]
	v_mfma_f32_16x16x32_bf16 v[42:45], v[126:129], v[236:239], v[42:45]
	v_mfma_f32_16x16x32_bf16 v[38:41], v[142:145], v[236:239], v[38:41]
	v_mfma_f32_16x16x32_bf16 v[22:25], v[126:129], v[244:247], v[22:25]
	v_mfma_f32_16x16x32_bf16 v[18:21], v[142:145], v[244:247], v[18:21]
	v_mfma_f32_16x16x32_bf16 v[74:77], v[130:133], v[224:227], v[74:77]
	v_mfma_f32_16x16x32_bf16 v[70:73], v[146:149], v[224:227], v[70:73]
	v_mfma_f32_16x16x32_bf16 v[58:61], v[130:133], v[232:235], v[58:61]
	v_mfma_f32_16x16x32_bf16 v[54:57], v[146:149], v[232:235], v[54:57]
	v_mfma_f32_16x16x32_bf16 v[42:45], v[130:133], v[240:243], v[42:45]
	v_mfma_f32_16x16x32_bf16 v[38:41], v[146:149], v[240:243], v[38:41]
	v_mfma_f32_16x16x32_bf16 v[22:25], v[130:133], v[248:251], v[22:25]
	v_mfma_f32_16x16x32_bf16 v[18:21], v[146:149], v[248:251], v[18:21]
	v_mfma_f32_16x16x32_bf16 v[50:53], v[166:169], v[220:223], v[50:53]
	v_mfma_f32_16x16x32_bf16 v[46:49], v[208:211], v[220:223], v[46:49]
	v_mfma_f32_16x16x32_bf16 v[34:37], v[166:169], v[228:231], v[34:37]
	v_mfma_f32_16x16x32_bf16 v[30:33], v[208:211], v[228:231], v[30:33]
	v_mfma_f32_16x16x32_bf16 v[26:29], v[166:169], v[236:239], v[26:29]
	v_mfma_f32_16x16x32_bf16 v[2:5], v[208:211], v[236:239], v[2:5]
	v_mfma_f32_16x16x32_bf16 v[12:15], v[166:169], v[244:247], v[12:15]
	v_mfma_f32_16x16x32_bf16 v[6:9], v[208:211], v[244:247], v[8:11]
	v_mfma_f32_16x16x32_bf16 v[50:53], v[204:207], v[224:227], v[50:53]
	v_mfma_f32_16x16x32_bf16 v[46:49], v[216:219], v[224:227], v[46:49]
	v_mfma_f32_16x16x32_bf16 v[34:37], v[204:207], v[232:235], v[34:37]
	v_mfma_f32_16x16x32_bf16 v[30:33], v[216:219], v[232:235], v[30:33]
	v_mfma_f32_16x16x32_bf16 v[26:29], v[204:207], v[240:243], v[26:29]
	v_mfma_f32_16x16x32_bf16 v[2:5], v[216:219], v[240:243], v[2:5]
	v_mfma_f32_16x16x32_bf16 v[12:15], v[204:207], v[248:251], v[12:15]
	v_mfma_f32_16x16x32_bf16 v[6:9], v[216:219], v[248:251], v[6:9]
	s_barrier
	s_add_i32 s52, 0, 0x18000
	v_add_u32_e32 v10, s52, v172
	s_add_i32 s53, 0, 0x1c000
	ds_read_b128 v[126:129], v10
	ds_read_b128 v[130:133], v10 offset:1024
	ds_read_b128 v[142:145], v10 offset:2048
	ds_read_b128 v[146:149], v10 offset:3072
	v_add_u32_e32 v10, s53, v172
	ds_read_b128 v[166:169], v10
	ds_read_b128 v[204:207], v10 offset:1024
	ds_read_b128 v[208:211], v10 offset:2048
	ds_read_b128 v[216:219], v10 offset:3072
	s_add_u32 s46, s46, 0x80000
	s_addc_u32 s47, s47, 0
	s_mov_b32 m0, s82
	v_lshl_add_u64 v[10:11], s[46:47], 0, v[150:151]
	ds_read_b128 v[220:223], v198 offset:32768
	ds_read_b128 v[224:227], v198 offset:33792
	ds_read_b128 v[228:231], v198 offset:34816
	ds_read_b128 v[232:235], v198 offset:35840
	ds_read_b128 v[236:239], v198 offset:36864
	ds_read_b128 v[240:243], v198 offset:37888
	ds_read_b128 v[244:247], v198 offset:38912
	ds_read_b128 v[248:251], v198 offset:39936
	global_load_lds_dwordx4 v[10:11], off
	v_lshl_add_u64 v[10:11], s[46:47], 0, v[152:153]
	s_mov_b32 m0, s83
	s_nop 0
	global_load_lds_dwordx4 v[10:11], off
	s_waitcnt vmcnt(8)
	s_waitcnt lgkmcnt(0)
	s_barrier
	v_mfma_f32_16x16x32_bf16 v[138:141], v[126:129], v[220:223], v[138:141]
	v_mfma_f32_16x16x32_bf16 v[134:137], v[142:145], v[220:223], v[134:137]
	v_mfma_f32_16x16x32_bf16 v[122:125], v[126:129], v[228:231], v[122:125]
	v_mfma_f32_16x16x32_bf16 v[118:121], v[142:145], v[228:231], v[118:121]
	v_mfma_f32_16x16x32_bf16 v[106:109], v[126:129], v[236:239], v[106:109]
	v_mfma_f32_16x16x32_bf16 v[102:105], v[142:145], v[236:239], v[102:105]
	v_mfma_f32_16x16x32_bf16 v[90:93], v[126:129], v[244:247], v[90:93]
	v_mfma_f32_16x16x32_bf16 v[86:89], v[142:145], v[244:247], v[86:89]
	v_mfma_f32_16x16x32_bf16 v[138:141], v[130:133], v[224:227], v[138:141]
	v_mfma_f32_16x16x32_bf16 v[134:137], v[146:149], v[224:227], v[134:137]
	v_mfma_f32_16x16x32_bf16 v[122:125], v[130:133], v[232:235], v[122:125]
	v_mfma_f32_16x16x32_bf16 v[118:121], v[146:149], v[232:235], v[118:121]
	v_mfma_f32_16x16x32_bf16 v[106:109], v[130:133], v[240:243], v[106:109]
	v_mfma_f32_16x16x32_bf16 v[102:105], v[146:149], v[240:243], v[102:105]
	v_mfma_f32_16x16x32_bf16 v[90:93], v[130:133], v[248:251], v[90:93]
	v_mfma_f32_16x16x32_bf16 v[86:89], v[146:149], v[248:251], v[86:89]
	v_mfma_f32_16x16x32_bf16 v[114:117], v[166:169], v[220:223], v[114:117]
	v_mfma_f32_16x16x32_bf16 v[110:113], v[208:211], v[220:223], v[110:113]
	v_mfma_f32_16x16x32_bf16 v[98:101], v[166:169], v[228:231], v[98:101]
	v_mfma_f32_16x16x32_bf16 v[94:97], v[208:211], v[228:231], v[94:97]
	v_mfma_f32_16x16x32_bf16 v[82:85], v[166:169], v[236:239], v[82:85]
	v_mfma_f32_16x16x32_bf16 v[78:81], v[208:211], v[236:239], v[78:81]
	v_mfma_f32_16x16x32_bf16 v[66:69], v[166:169], v[244:247], v[66:69]
	v_mfma_f32_16x16x32_bf16 v[62:65], v[208:211], v[244:247], v[62:65]
	v_mfma_f32_16x16x32_bf16 v[114:117], v[204:207], v[224:227], v[114:117]
	v_mfma_f32_16x16x32_bf16 v[110:113], v[216:219], v[224:227], v[110:113]
	v_mfma_f32_16x16x32_bf16 v[98:101], v[204:207], v[232:235], v[98:101]
	v_mfma_f32_16x16x32_bf16 v[94:97], v[216:219], v[232:235], v[94:97]
	v_mfma_f32_16x16x32_bf16 v[82:85], v[204:207], v[240:243], v[82:85]
	v_mfma_f32_16x16x32_bf16 v[78:81], v[216:219], v[240:243], v[78:81]
	v_mfma_f32_16x16x32_bf16 v[66:69], v[204:207], v[248:251], v[66:69]
	v_mfma_f32_16x16x32_bf16 v[62:65], v[216:219], v[248:251], v[62:65]
	s_barrier
	s_add_i32 s46, s52, s33
	v_lshl_add_u64 v[10:11], v[170:171], 0, s[36:37]
	s_mov_b32 m0, s46
	ds_read_b128 v[220:223], v198 offset:49152
	ds_read_b128 v[224:227], v198 offset:50176
	ds_read_b128 v[228:231], v198 offset:51200
	ds_read_b128 v[232:235], v198 offset:52224
	ds_read_b128 v[236:239], v198 offset:53248
	ds_read_b128 v[240:243], v198 offset:54272
	ds_read_b128 v[244:247], v198 offset:55296
	ds_read_b128 v[248:251], v198 offset:56320
	global_load_lds_dwordx4 v[10:11], off
	s_add_i32 m0, s46, 0x2000
	s_add_u32 s24, s24, 0x80080
	v_lshl_add_u64 v[10:11], v[200:201], 0, s[36:37]
	s_addc_u32 s25, s25, 0
	s_add_i32 s46, s53, s33
	global_load_lds_dwordx4 v[10:11], off
	v_lshl_add_u64 v[10:11], s[24:25], 0, v[0:1]
	s_mov_b32 m0, s46
	s_nop 0
	global_load_lds_dwordx4 v[10:11], off
	v_lshl_add_u64 v[10:11], s[24:25], 0, v[154:155]
	s_add_i32 m0, s46, 0x2000
	s_nop 0
	global_load_lds_dwordx4 v[10:11], off
	v_lshl_add_u64 v[10:11], v[202:203], 0, s[36:37]
	s_mov_b32 m0, s94
	s_nop 0
	global_load_lds_dwordx4 v[10:11], off
	v_lshl_add_u64 v[10:11], v[212:213], 0, s[36:37]
	s_mov_b32 m0, s95
	s_nop 0
	global_load_lds_dwordx4 v[10:11], off
	s_waitcnt vmcnt(8)
	s_waitcnt lgkmcnt(0)
	s_barrier
	v_mfma_f32_16x16x32_bf16 v[74:77], v[126:129], v[220:223], v[74:77]
	v_mfma_f32_16x16x32_bf16 v[70:73], v[142:145], v[220:223], v[70:73]
	v_mfma_f32_16x16x32_bf16 v[58:61], v[126:129], v[228:231], v[58:61]
	v_mfma_f32_16x16x32_bf16 v[54:57], v[142:145], v[228:231], v[54:57]
	v_mfma_f32_16x16x32_bf16 v[42:45], v[126:129], v[236:239], v[42:45]
	v_mfma_f32_16x16x32_bf16 v[38:41], v[142:145], v[236:239], v[38:41]
	v_mfma_f32_16x16x32_bf16 v[22:25], v[126:129], v[244:247], v[22:25]
	v_mfma_f32_16x16x32_bf16 v[18:21], v[142:145], v[244:247], v[18:21]
	v_mfma_f32_16x16x32_bf16 v[74:77], v[130:133], v[224:227], v[74:77]
	v_mfma_f32_16x16x32_bf16 v[70:73], v[146:149], v[224:227], v[70:73]
	v_mfma_f32_16x16x32_bf16 v[58:61], v[130:133], v[232:235], v[58:61]
	v_mfma_f32_16x16x32_bf16 v[54:57], v[146:149], v[232:235], v[54:57]
	v_mfma_f32_16x16x32_bf16 v[42:45], v[130:133], v[240:243], v[42:45]
	v_mfma_f32_16x16x32_bf16 v[38:41], v[146:149], v[240:243], v[38:41]
	v_mfma_f32_16x16x32_bf16 v[22:25], v[130:133], v[248:251], v[22:25]
	v_mfma_f32_16x16x32_bf16 v[18:21], v[146:149], v[248:251], v[18:21]
	v_mfma_f32_16x16x32_bf16 v[50:53], v[166:169], v[220:223], v[50:53]
	v_mfma_f32_16x16x32_bf16 v[46:49], v[208:211], v[220:223], v[46:49]
	v_mfma_f32_16x16x32_bf16 v[34:37], v[166:169], v[228:231], v[34:37]
	v_mfma_f32_16x16x32_bf16 v[30:33], v[208:211], v[228:231], v[30:33]
	v_mfma_f32_16x16x32_bf16 v[26:29], v[166:169], v[236:239], v[26:29]
	v_mfma_f32_16x16x32_bf16 v[2:5], v[208:211], v[236:239], v[2:5]
	v_mfma_f32_16x16x32_bf16 v[10:13], v[166:169], v[244:247], v[12:15]
	v_mfma_f32_16x16x32_bf16 v[6:9], v[208:211], v[244:247], v[6:9]
	v_mfma_f32_16x16x32_bf16 v[50:53], v[204:207], v[224:227], v[50:53]
	v_mfma_f32_16x16x32_bf16 v[46:49], v[216:219], v[224:227], v[46:49]
	v_mfma_f32_16x16x32_bf16 v[34:37], v[204:207], v[232:235], v[34:37]
	v_mfma_f32_16x16x32_bf16 v[30:33], v[216:219], v[232:235], v[30:33]
	v_mfma_f32_16x16x32_bf16 v[26:29], v[204:207], v[240:243], v[26:29]
	v_mfma_f32_16x16x32_bf16 v[2:5], v[216:219], v[240:243], v[2:5]
	v_mfma_f32_16x16x32_bf16 v[12:15], v[204:207], v[248:251], v[10:13]
	v_mfma_f32_16x16x32_bf16 v[8:11], v[216:219], v[248:251], v[6:9]
	s_barrier
	s_add_i32 s51, s51, 2
	s_add_u32 s18, s18, 0x100
	s_addc_u32 s19, s19, 0
	s_add_u32 s29, s29, 0x100
	s_addc_u32 s50, s50, 0
	s_cmp_gt_u32 s51, 29
	s_cbranch_scc0 .LBB0_164
	s_setprio 0
	s_and_b64 vcc, exec, s[10:11]
	s_cbranch_vccz .LBB0_167
	s_barrier

.LBB0_755:
	s_ashr_i32 s21, s20, 31
	s_lshl_b64 s[22:23], s[20:21], 20
	s_add_u32 s22, s66, s22
	s_addc_u32 s23, s67, s23
	s_and_b64 s[24:25], s[40:41], exec
	s_cselect_b32 s1, s23, s43
	s_cselect_b32 s21, s22, s42
	s_ashr_i32 s19, s18, 31
	s_lshl_b64 s[24:25], s[18:19], 20
	s_add_u32 s24, s12, s24
	s_addc_u32 s25, s15, s25
	s_and_b64 s[46:47], s[40:41], exec
	s_cselect_b32 s19, s25, s45
	s_cselect_b32 s27, s24, s44
	s_add_u32 s42, s42, 0x80080
	s_addc_u32 s43, s43, 0
	s_add_u32 s29, s44, 0x100
	v_mov_b32_e32 v2, 0
	s_addc_u32 s51, s45, 0
	s_mov_b32 s61, -2
	v_mov_b32_e32 v3, v2
	v_mov_b32_e32 v4, v2
	v_mov_b32_e32 v5, v2
	v_mov_b32_e32 v6, v2
	v_mov_b32_e32 v7, v2
	v_mov_b32_e32 v8, v2
	v_mov_b32_e32 v9, v2
	v_mov_b32_e32 v22, v2
	v_mov_b32_e32 v23, v2
	v_mov_b32_e32 v24, v2
	v_mov_b32_e32 v25, v2
	v_mov_b32_e32 v26, v2
	v_mov_b32_e32 v27, v2
	v_mov_b32_e32 v28, v2
	v_mov_b32_e32 v29, v2
	v_mov_b32_e32 v38, v2
	v_mov_b32_e32 v39, v2
	v_mov_b32_e32 v40, v2
	v_mov_b32_e32 v41, v2
	v_mov_b32_e32 v42, v2
	v_mov_b32_e32 v43, v2
	v_mov_b32_e32 v44, v2
	v_mov_b32_e32 v45, v2
	v_mov_b32_e32 v54, v2
	v_mov_b32_e32 v55, v2
	v_mov_b32_e32 v56, v2
	v_mov_b32_e32 v57, v2
	v_mov_b32_e32 v58, v2
	v_mov_b32_e32 v59, v2
	v_mov_b32_e32 v60, v2
	v_mov_b32_e32 v61, v2
	v_mov_b32_e32 v10, v2
	v_mov_b32_e32 v11, v2
	v_mov_b32_e32 v12, v2
	v_mov_b32_e32 v13, v2
	v_mov_b32_e32 v18, v2
	v_mov_b32_e32 v19, v2
	v_mov_b32_e32 v20, v2
	v_mov_b32_e32 v21, v2
	v_mov_b32_e32 v30, v2
	v_mov_b32_e32 v31, v2
	v_mov_b32_e32 v32, v2
	v_mov_b32_e32 v33, v2
	v_mov_b32_e32 v34, v2
	v_mov_b32_e32 v35, v2
	v_mov_b32_e32 v36, v2
	v_mov_b32_e32 v37, v2
	v_mov_b32_e32 v46, v2
	v_mov_b32_e32 v47, v2
	v_mov_b32_e32 v48, v2
	v_mov_b32_e32 v49, v2
	v_mov_b32_e32 v50, v2
	v_mov_b32_e32 v51, v2
	v_mov_b32_e32 v52, v2
	v_mov_b32_e32 v53, v2
	v_mov_b32_e32 v62, v2
	v_mov_b32_e32 v63, v2
	v_mov_b32_e32 v64, v2
	v_mov_b32_e32 v65, v2
	v_mov_b32_e32 v66, v2
	v_mov_b32_e32 v67, v2
	v_mov_b32_e32 v68, v2
	v_mov_b32_e32 v69, v2
	v_mov_b32_e32 v70, v2
	v_mov_b32_e32 v71, v2
	v_mov_b32_e32 v72, v2
	v_mov_b32_e32 v73, v2
	v_mov_b32_e32 v74, v2
	v_mov_b32_e32 v75, v2
	v_mov_b32_e32 v76, v2
	v_mov_b32_e32 v77, v2
	v_mov_b32_e32 v86, v2
	v_mov_b32_e32 v87, v2
	v_mov_b32_e32 v88, v2
	v_mov_b32_e32 v89, v2
	v_mov_b32_e32 v90, v2
	v_mov_b32_e32 v91, v2
	v_mov_b32_e32 v92, v2
	v_mov_b32_e32 v93, v2
	v_mov_b32_e32 v102, v2
	v_mov_b32_e32 v103, v2
	v_mov_b32_e32 v104, v2
	v_mov_b32_e32 v105, v2
	v_mov_b32_e32 v106, v2
	v_mov_b32_e32 v107, v2
	v_mov_b32_e32 v108, v2
	v_mov_b32_e32 v109, v2
	v_mov_b32_e32 v118, v2
	v_mov_b32_e32 v119, v2
	v_mov_b32_e32 v120, v2
	v_mov_b32_e32 v121, v2
	v_mov_b32_e32 v122, v2
	v_mov_b32_e32 v123, v2
	v_mov_b32_e32 v124, v2
	v_mov_b32_e32 v125, v2
	v_mov_b32_e32 v78, v2
	v_mov_b32_e32 v79, v2
	v_mov_b32_e32 v80, v2
	v_mov_b32_e32 v81, v2
	v_mov_b32_e32 v82, v2
	v_mov_b32_e32 v83, v2
	v_mov_b32_e32 v84, v2
	v_mov_b32_e32 v85, v2
	v_mov_b32_e32 v94, v2
	v_mov_b32_e32 v95, v2
	v_mov_b32_e32 v96, v2
	v_mov_b32_e32 v97, v2
	v_mov_b32_e32 v98, v2
	v_mov_b32_e32 v99, v2
	v_mov_b32_e32 v100, v2
	v_mov_b32_e32 v101, v2
	v_mov_b32_e32 v110, v2
	v_mov_b32_e32 v111, v2
	v_mov_b32_e32 v112, v2
	v_mov_b32_e32 v113, v2
	v_mov_b32_e32 v114, v2
	v_mov_b32_e32 v115, v2
	v_mov_b32_e32 v116, v2
	v_mov_b32_e32 v117, v2
	v_mov_b32_e32 v126, v2
	v_mov_b32_e32 v127, v2
	v_mov_b32_e32 v128, v2
	v_mov_b32_e32 v129, v2
	v_mov_b32_e32 v130, v2
	v_mov_b32_e32 v131, v2
	v_mov_b32_e32 v132, v2
	v_mov_b32_e32 v133, v2
	s_waitcnt vmcnt(0)
	v_readfirstlane_b32 vcc_lo, v252
	s_nop 0
	s_cmpk_ge_u32 vcc_lo, 0x100
	s_cbranch_scc0 .Lsprio2
	s_setprio 1
.Lsprio2:
.LBB0_756:
	s_add_u32 s44, s42, 0xfff80080
	s_addc_u32 s45, s43, -1
	s_add_i32 s62, 0, 0x10000
	s_cmp_eq_u32 s61, 28
	s_cselect_b32 s47, s1, s45
	s_cselect_b32 s46, s21, s44
	v_add_u32_e32 v146, s62, v148
	s_cselect_b32 s45, s19, s51
	s_cselect_b32 s44, s27, s29
	s_add_i32 s64, 0, 0x14000
	ds_read_b128 v[138:141], v146
	ds_read_b128 v[142:145], v146 offset:1024
	ds_read_b128 v[154:157], v146 offset:2048
	ds_read_b128 v[158:161], v146 offset:3072
	v_add_u32_e32 v146, s64, v148
	ds_read_b128 v[162:165], v146
	ds_read_b128 v[166:169], v146 offset:1024
	ds_read_b128 v[170:173], v146 offset:2048
	ds_read_b128 v[174:177], v146 offset:3072
	v_lshl_add_u64 v[146:147], s[42:43], 0, v[134:135]
	s_add_i32 m0, s50, 0xc000
	ds_read_b128 v[178:181], v152
	ds_read_b128 v[182:185], v152 offset:1024
	ds_read_b128 v[186:189], v152 offset:2048
	ds_read_b128 v[190:193], v152 offset:3072
	ds_read_b128 v[194:197], v152 offset:4096
	ds_read_b128 v[198:201], v152 offset:5120
	ds_read_b128 v[202:205], v152 offset:6144
	ds_read_b128 v[206:209], v152 offset:7168
	global_load_lds_dwordx4 v[146:147], off
	v_lshl_add_u64 v[146:147], s[42:43], 0, v[136:137]
	s_add_i32 m0, s50, 0xe000
	s_nop 0
	global_load_lds_dwordx4 v[146:147], off
	s_waitcnt vmcnt(8)
	s_waitcnt lgkmcnt(0)
	s_barrier
	v_mfma_f32_16x16x32_bf16 v[130:133], v[138:141], v[178:181], v[130:133]
	v_mfma_f32_16x16x32_bf16 v[126:129], v[154:157], v[178:181], v[126:129]
	v_mfma_f32_16x16x32_bf16 v[114:117], v[138:141], v[186:189], v[114:117]
	v_mfma_f32_16x16x32_bf16 v[110:113], v[154:157], v[186:189], v[110:113]
	v_mfma_f32_16x16x32_bf16 v[98:101], v[138:141], v[194:197], v[98:101]
	v_mfma_f32_16x16x32_bf16 v[94:97], v[154:157], v[194:197], v[94:97]
	v_mfma_f32_16x16x32_bf16 v[82:85], v[138:141], v[202:205], v[82:85]
	v_mfma_f32_16x16x32_bf16 v[78:81], v[154:157], v[202:205], v[78:81]
	v_mfma_f32_16x16x32_bf16 v[130:133], v[142:145], v[182:185], v[130:133]
	v_mfma_f32_16x16x32_bf16 v[126:129], v[158:161], v[182:185], v[126:129]
	v_mfma_f32_16x16x32_bf16 v[114:117], v[142:145], v[190:193], v[114:117]
	v_mfma_f32_16x16x32_bf16 v[110:113], v[158:161], v[190:193], v[110:113]
	v_mfma_f32_16x16x32_bf16 v[98:101], v[142:145], v[198:201], v[98:101]
	v_mfma_f32_16x16x32_bf16 v[94:97], v[158:161], v[198:201], v[94:97]
	v_mfma_f32_16x16x32_bf16 v[82:85], v[142:145], v[206:209], v[82:85]
	v_mfma_f32_16x16x32_bf16 v[78:81], v[158:161], v[206:209], v[78:81]
	v_mfma_f32_16x16x32_bf16 v[122:125], v[162:165], v[178:181], v[122:125]
	v_mfma_f32_16x16x32_bf16 v[118:121], v[170:173], v[178:181], v[118:121]
	v_mfma_f32_16x16x32_bf16 v[106:109], v[162:165], v[186:189], v[106:109]
	v_mfma_f32_16x16x32_bf16 v[102:105], v[170:173], v[186:189], v[102:105]
	v_mfma_f32_16x16x32_bf16 v[90:93], v[162:165], v[194:197], v[90:93]
	v_mfma_f32_16x16x32_bf16 v[86:89], v[170:173], v[194:197], v[86:89]
	v_mfma_f32_16x16x32_bf16 v[74:77], v[162:165], v[202:205], v[74:77]
	v_mfma_f32_16x16x32_bf16 v[70:73], v[170:173], v[202:205], v[70:73]
	v_mfma_f32_16x16x32_bf16 v[122:125], v[166:169], v[182:185], v[122:125]
	v_mfma_f32_16x16x32_bf16 v[118:121], v[174:177], v[182:185], v[118:121]
	v_mfma_f32_16x16x32_bf16 v[106:109], v[166:169], v[190:193], v[106:109]
	v_mfma_f32_16x16x32_bf16 v[102:105], v[174:177], v[190:193], v[102:105]
	v_mfma_f32_16x16x32_bf16 v[90:93], v[166:169], v[198:201], v[90:93]
	v_mfma_f32_16x16x32_bf16 v[86:89], v[174:177], v[198:201], v[86:89]
	v_mfma_f32_16x16x32_bf16 v[74:77], v[166:169], v[206:209], v[74:77]
	v_mfma_f32_16x16x32_bf16 v[70:73], v[174:177], v[206:209], v[70:73]
	s_barrier
	s_add_i32 s62, s62, s33
	v_lshl_add_u64 v[146:147], s[44:45], 0, v[0:1]
	s_mov_b32 m0, s62
	ds_read_b128 v[178:181], v152 offset:16384
	ds_read_b128 v[182:185], v152 offset:17408
	ds_read_b128 v[186:189], v152 offset:18432
	ds_read_b128 v[190:193], v152 offset:19456
	ds_read_b128 v[194:197], v152 offset:20480
	ds_read_b128 v[198:201], v152 offset:21504
	ds_read_b128 v[202:205], v152 offset:22528
	ds_read_b128 v[206:209], v152 offset:23552
	global_load_lds_dwordx4 v[146:147], off
	s_add_i32 m0, s62, 0x2000
	s_add_u32 s62, s44, 0x80000
	v_lshl_add_u64 v[210:211], s[44:45], 0, v[14:15]
	s_addc_u32 s63, s45, 0
	s_add_i32 s64, s64, s33
	global_load_lds_dwordx4 v[210:211], off
	v_lshl_add_u64 v[212:213], s[62:63], 0, v[0:1]
	s_mov_b32 m0, s64
	v_lshl_add_u64 v[214:215], s[46:47], 0, v[14:15]
	global_load_lds_dwordx4 v[212:213], off
	v_lshl_add_u64 v[212:213], s[62:63], 0, v[14:15]
	s_add_i32 m0, s64, 0x2000
	s_nop 0
	global_load_lds_dwordx4 v[212:213], off
	v_lshl_add_u64 v[212:213], s[46:47], 0, v[0:1]
	s_mov_b32 m0, s50
	s_nop 0
	global_load_lds_dwordx4 v[212:213], off
	s_mov_b32 m0, s52
	s_nop 0
	global_load_lds_dwordx4 v[214:215], off
	s_waitcnt vmcnt(8)
	s_waitcnt lgkmcnt(0)
	s_barrier
	v_mfma_f32_16x16x32_bf16 v[66:69], v[138:141], v[178:181], v[66:69]
	v_mfma_f32_16x16x32_bf16 v[62:65], v[154:157], v[178:181], v[62:65]
	v_mfma_f32_16x16x32_bf16 v[50:53], v[138:141], v[186:189], v[50:53]
	v_mfma_f32_16x16x32_bf16 v[46:49], v[154:157], v[186:189], v[46:49]
	v_mfma_f32_16x16x32_bf16 v[34:37], v[138:141], v[194:197], v[34:37]
	v_mfma_f32_16x16x32_bf16 v[30:33], v[154:157], v[194:197], v[30:33]
	v_mfma_f32_16x16x32_bf16 v[18:21], v[138:141], v[202:205], v[18:21]
	v_mfma_f32_16x16x32_bf16 v[10:13], v[154:157], v[202:205], v[10:13]
	v_mfma_f32_16x16x32_bf16 v[66:69], v[142:145], v[182:185], v[66:69]
	v_mfma_f32_16x16x32_bf16 v[62:65], v[158:161], v[182:185], v[62:65]
	v_mfma_f32_16x16x32_bf16 v[50:53], v[142:145], v[190:193], v[50:53]
	v_mfma_f32_16x16x32_bf16 v[46:49], v[158:161], v[190:193], v[46:49]
	v_mfma_f32_16x16x32_bf16 v[34:37], v[142:145], v[198:201], v[34:37]
	v_mfma_f32_16x16x32_bf16 v[30:33], v[158:161], v[198:201], v[30:33]
	v_mfma_f32_16x16x32_bf16 v[18:21], v[142:145], v[206:209], v[18:21]
	v_mfma_f32_16x16x32_bf16 v[10:13], v[158:161], v[206:209], v[10:13]
	v_mfma_f32_16x16x32_bf16 v[58:61], v[162:165], v[178:181], v[58:61]
	v_mfma_f32_16x16x32_bf16 v[54:57], v[170:173], v[178:181], v[54:57]
	v_mfma_f32_16x16x32_bf16 v[42:45], v[162:165], v[186:189], v[42:45]
	v_mfma_f32_16x16x32_bf16 v[38:41], v[170:173], v[186:189], v[38:41]
	v_mfma_f32_16x16x32_bf16 v[26:29], v[162:165], v[194:197], v[26:29]
	v_mfma_f32_16x16x32_bf16 v[22:25], v[170:173], v[194:197], v[22:25]
	v_mfma_f32_16x16x32_bf16 v[6:9], v[162:165], v[202:205], v[6:9]
	v_mfma_f32_16x16x32_bf16 v[2:5], v[170:173], v[202:205], v[2:5]
	v_mfma_f32_16x16x32_bf16 v[58:61], v[166:169], v[182:185], v[58:61]
	v_mfma_f32_16x16x32_bf16 v[54:57], v[174:177], v[182:185], v[54:57]
	v_mfma_f32_16x16x32_bf16 v[42:45], v[166:169], v[190:193], v[42:45]
	v_mfma_f32_16x16x32_bf16 v[38:41], v[174:177], v[190:193], v[38:41]
	v_mfma_f32_16x16x32_bf16 v[26:29], v[166:169], v[198:201], v[26:29]
	v_mfma_f32_16x16x32_bf16 v[22:25], v[174:177], v[198:201], v[22:25]
	v_mfma_f32_16x16x32_bf16 v[6:9], v[166:169], v[206:209], v[6:9]
	v_mfma_f32_16x16x32_bf16 v[2:5], v[174:177], v[206:209], v[2:5]
	s_barrier
	s_add_i32 s62, 0, 0x18000
	s_add_i32 s63, 0, 0x1c000
	v_add_u32_e32 v158, s62, v148
	v_add_u32_e32 v174, s63, v148
	ds_read_b128 v[138:141], v158
	ds_read_b128 v[142:145], v158 offset:1024
	ds_read_b128 v[154:157], v158 offset:2048
	ds_read_b128 v[158:161], v158 offset:3072
	ds_read_b128 v[162:165], v174
	ds_read_b128 v[166:169], v174 offset:1024
	ds_read_b128 v[170:173], v174 offset:2048
	ds_read_b128 v[174:177], v174 offset:3072
	s_add_u32 s46, s46, 0x80000
	s_addc_u32 s47, s47, 0
	s_mov_b32 m0, s53
	v_lshl_add_u64 v[216:217], s[46:47], 0, v[0:1]
	ds_read_b128 v[178:181], v152 offset:32768
	ds_read_b128 v[182:185], v152 offset:33792
	ds_read_b128 v[186:189], v152 offset:34816
	ds_read_b128 v[190:193], v152 offset:35840
	ds_read_b128 v[194:197], v152 offset:36864
	ds_read_b128 v[198:201], v152 offset:37888
	ds_read_b128 v[202:205], v152 offset:38912
	ds_read_b128 v[206:209], v152 offset:39936
	global_load_lds_dwordx4 v[216:217], off
	v_lshl_add_u64 v[216:217], s[46:47], 0, v[14:15]
	s_mov_b32 m0, s54
	s_nop 0
	global_load_lds_dwordx4 v[216:217], off
	s_waitcnt vmcnt(8)
	s_waitcnt lgkmcnt(0)
	s_barrier
	v_mfma_f32_16x16x32_bf16 v[130:133], v[138:141], v[178:181], v[130:133]
	v_mfma_f32_16x16x32_bf16 v[126:129], v[154:157], v[178:181], v[126:129]
	v_mfma_f32_16x16x32_bf16 v[114:117], v[138:141], v[186:189], v[114:117]
	v_mfma_f32_16x16x32_bf16 v[110:113], v[154:157], v[186:189], v[110:113]
	v_mfma_f32_16x16x32_bf16 v[98:101], v[138:141], v[194:197], v[98:101]
	v_mfma_f32_16x16x32_bf16 v[94:97], v[154:157], v[194:197], v[94:97]
	v_mfma_f32_16x16x32_bf16 v[82:85], v[138:141], v[202:205], v[82:85]
	v_mfma_f32_16x16x32_bf16 v[78:81], v[154:157], v[202:205], v[78:81]
	v_mfma_f32_16x16x32_bf16 v[130:133], v[142:145], v[182:185], v[130:133]
	v_mfma_f32_16x16x32_bf16 v[126:129], v[158:161], v[182:185], v[126:129]
	v_mfma_f32_16x16x32_bf16 v[114:117], v[142:145], v[190:193], v[114:117]
	v_mfma_f32_16x16x32_bf16 v[110:113], v[158:161], v[190:193], v[110:113]
	v_mfma_f32_16x16x32_bf16 v[98:101], v[142:145], v[198:201], v[98:101]
	v_mfma_f32_16x16x32_bf16 v[94:97], v[158:161], v[198:201], v[94:97]
	v_mfma_f32_16x16x32_bf16 v[82:85], v[142:145], v[206:209], v[82:85]
	v_mfma_f32_16x16x32_bf16 v[78:81], v[158:161], v[206:209], v[78:81]
	v_mfma_f32_16x16x32_bf16 v[122:125], v[162:165], v[178:181], v[122:125]
	v_mfma_f32_16x16x32_bf16 v[118:121], v[170:173], v[178:181], v[118:121]
	v_mfma_f32_16x16x32_bf16 v[106:109], v[162:165], v[186:189], v[106:109]
	v_mfma_f32_16x16x32_bf16 v[102:105], v[170:173], v[186:189], v[102:105]
	v_mfma_f32_16x16x32_bf16 v[90:93], v[162:165], v[194:197], v[90:93]
	v_mfma_f32_16x16x32_bf16 v[86:89], v[170:173], v[194:197], v[86:89]
	v_mfma_f32_16x16x32_bf16 v[74:77], v[162:165], v[202:205], v[74:77]
	v_mfma_f32_16x16x32_bf16 v[70:73], v[170:173], v[202:205], v[70:73]
	v_mfma_f32_16x16x32_bf16 v[122:125], v[166:169], v[182:185], v[122:125]
	v_mfma_f32_16x16x32_bf16 v[118:121], v[174:177], v[182:185], v[118:121]
	v_mfma_f32_16x16x32_bf16 v[106:109], v[166:169], v[190:193], v[106:109]
	v_mfma_f32_16x16x32_bf16 v[102:105], v[174:177], v[190:193], v[102:105]
	v_mfma_f32_16x16x32_bf16 v[90:93], v[166:169], v[198:201], v[90:93]
	v_mfma_f32_16x16x32_bf16 v[86:89], v[174:177], v[198:201], v[86:89]
	v_mfma_f32_16x16x32_bf16 v[74:77], v[166:169], v[206:209], v[74:77]
	v_mfma_f32_16x16x32_bf16 v[70:73], v[174:177], v[206:209], v[70:73]
	s_barrier
	s_add_i32 s46, s62, s33
	v_lshl_add_u64 v[146:147], v[146:147], 0, s[36:37]
	s_mov_b32 m0, s46
	ds_read_b128 v[178:181], v152 offset:49152
	ds_read_b128 v[182:185], v152 offset:50176
	ds_read_b128 v[186:189], v152 offset:51200
	ds_read_b128 v[190:193], v152 offset:52224
	ds_read_b128 v[194:197], v152 offset:53248
	ds_read_b128 v[198:201], v152 offset:54272
	ds_read_b128 v[202:205], v152 offset:55296
	ds_read_b128 v[206:209], v152 offset:56320
	global_load_lds_dwordx4 v[146:147], off
	s_add_i32 m0, s46, 0x2000
	s_add_u32 s44, s44, 0x80080
	v_lshl_add_u64 v[146:147], v[210:211], 0, s[36:37]
	s_addc_u32 s45, s45, 0
	s_add_i32 s46, s63, s33
	global_load_lds_dwordx4 v[146:147], off
	v_lshl_add_u64 v[146:147], s[44:45], 0, v[0:1]
	s_mov_b32 m0, s46
	s_nop 0
	global_load_lds_dwordx4 v[146:147], off
	v_lshl_add_u64 v[146:147], s[44:45], 0, v[14:15]
	s_add_i32 m0, s46, 0x2000
	s_nop 0
	global_load_lds_dwordx4 v[146:147], off
	v_lshl_add_u64 v[146:147], v[212:213], 0, s[36:37]
	s_mov_b32 m0, s56
	s_nop 0
	global_load_lds_dwordx4 v[146:147], off
	v_lshl_add_u64 v[146:147], v[214:215], 0, s[36:37]
	s_mov_b32 m0, s57
	s_nop 0
	global_load_lds_dwordx4 v[146:147], off
	s_waitcnt vmcnt(8)
	s_waitcnt lgkmcnt(0)
	s_barrier
	v_mfma_f32_16x16x32_bf16 v[66:69], v[138:141], v[178:181], v[66:69]
	v_mfma_f32_16x16x32_bf16 v[62:65], v[154:157], v[178:181], v[62:65]
	v_mfma_f32_16x16x32_bf16 v[50:53], v[138:141], v[186:189], v[50:53]
	v_mfma_f32_16x16x32_bf16 v[46:49], v[154:157], v[186:189], v[46:49]
	v_mfma_f32_16x16x32_bf16 v[34:37], v[138:141], v[194:197], v[34:37]
	v_mfma_f32_16x16x32_bf16 v[30:33], v[154:157], v[194:197], v[30:33]
	v_mfma_f32_16x16x32_bf16 v[18:21], v[138:141], v[202:205], v[18:21]
	v_mfma_f32_16x16x32_bf16 v[10:13], v[154:157], v[202:205], v[10:13]
	v_mfma_f32_16x16x32_bf16 v[66:69], v[142:145], v[182:185], v[66:69]
	v_mfma_f32_16x16x32_bf16 v[62:65], v[158:161], v[182:185], v[62:65]
	v_mfma_f32_16x16x32_bf16 v[50:53], v[142:145], v[190:193], v[50:53]
	v_mfma_f32_16x16x32_bf16 v[46:49], v[158:161], v[190:193], v[46:49]
	v_mfma_f32_16x16x32_bf16 v[34:37], v[142:145], v[198:201], v[34:37]
	v_mfma_f32_16x16x32_bf16 v[30:33], v[158:161], v[198:201], v[30:33]
	v_mfma_f32_16x16x32_bf16 v[18:21], v[142:145], v[206:209], v[18:21]
	v_mfma_f32_16x16x32_bf16 v[10:13], v[158:161], v[206:209], v[10:13]
	v_mfma_f32_16x16x32_bf16 v[58:61], v[162:165], v[178:181], v[58:61]
	v_mfma_f32_16x16x32_bf16 v[54:57], v[170:173], v[178:181], v[54:57]
	v_mfma_f32_16x16x32_bf16 v[42:45], v[162:165], v[186:189], v[42:45]
	v_mfma_f32_16x16x32_bf16 v[38:41], v[170:173], v[186:189], v[38:41]
	v_mfma_f32_16x16x32_bf16 v[26:29], v[162:165], v[194:197], v[26:29]
	v_mfma_f32_16x16x32_bf16 v[22:25], v[170:173], v[194:197], v[22:25]
	v_mfma_f32_16x16x32_bf16 v[6:9], v[162:165], v[202:205], v[6:9]
	v_mfma_f32_16x16x32_bf16 v[2:5], v[170:173], v[202:205], v[2:5]
	v_mfma_f32_16x16x32_bf16 v[58:61], v[166:169], v[182:185], v[58:61]
	v_mfma_f32_16x16x32_bf16 v[54:57], v[174:177], v[182:185], v[54:57]
	v_mfma_f32_16x16x32_bf16 v[42:45], v[166:169], v[190:193], v[42:45]
	v_mfma_f32_16x16x32_bf16 v[38:41], v[174:177], v[190:193], v[38:41]
	v_mfma_f32_16x16x32_bf16 v[26:29], v[166:169], v[198:201], v[26:29]
	v_mfma_f32_16x16x32_bf16 v[22:25], v[174:177], v[198:201], v[22:25]
	v_mfma_f32_16x16x32_bf16 v[6:9], v[166:169], v[206:209], v[6:9]
	v_mfma_f32_16x16x32_bf16 v[2:5], v[174:177], v[206:209], v[2:5]
	s_barrier
	s_add_i32 s61, s61, 2
	s_add_u32 s42, s42, 0x100
	s_addc_u32 s43, s43, 0
	s_add_u32 s29, s29, 0x100
	s_addc_u32 s51, s51, 0
	s_cmp_gt_u32 s61, 29
	s_cbranch_scc0 .LBB0_756
	s_setprio 0
	s_and_b64 vcc, exec, s[10:11]
	s_cbranch_vccz .LBB0_759
	s_barrier

.LBB0_877:
	s_ashr_i32 s7, s6, 31
	s_lshl_b64 s[10:11], s[6:7], 20
	s_cmp_eq_u32 s1, 0
	s_cselect_b32 s7, s90, s19
	s_cselect_b32 s5, s91, s18
	s_cselect_b32 s26, s93, s92
	s_cselect_b32 s27, s16, s55
	s_add_u32 s10, s7, s10
	s_addc_u32 s11, s5, s11
	s_and_b64 s[22:23], s[44:45], exec
	s_cselect_b32 s7, s11, s9
	s_cselect_b32 s25, s10, s8
	s_ashr_i32 s5, s4, 31
	s_lshl_b64 s[22:23], s[4:5], 20
	s_add_u32 s26, s26, s22
	s_addc_u32 s27, s27, s23
	s_and_b64 s[22:23], s[44:45], exec
	s_cselect_b32 s5, s27, s21
	s_cselect_b32 s47, s26, s20
	s_add_u32 s8, s8, 0x80080
	s_addc_u32 s9, s9, 0
	s_add_u32 s50, s20, 0x100
	v_mov_b32_e32 v8, 0
	v_mov_b32_e32 v212, 0x7f800000
	v_mov_b32_e32 v197, 0x358637bd
	s_addc_u32 s51, s21, 0
	s_mov_b32 s52, -2
	v_mov_b32_e32 v9, v8
	s_waitcnt vmcnt(0)
	v_mov_b32_e32 v10, v8
	v_mov_b32_e32 v11, v8
	v_mov_b32_e32 v12, v8
	v_mov_b32_e32 v13, v8
	v_mov_b32_e32 v14, v8
	v_mov_b32_e32 v15, v8
	v_mov_b32_e32 v2, v8
	v_mov_b32_e32 v3, v8
	v_mov_b32_e32 v4, v8
	v_mov_b32_e32 v5, v8
	v_mov_b32_e32 v26, v8
	v_mov_b32_e32 v27, v8
	v_mov_b32_e32 v28, v8
	v_mov_b32_e32 v29, v8
	v_mov_b32_e32 v30, v8
	v_mov_b32_e32 v31, v8
	v_mov_b32_e32 v32, v8
	v_mov_b32_e32 v33, v8
	v_mov_b32_e32 v34, v8
	v_mov_b32_e32 v35, v8
	v_mov_b32_e32 v36, v8
	v_mov_b32_e32 v37, v8
	v_mov_b32_e32 v46, v8
	v_mov_b32_e32 v47, v8
	v_mov_b32_e32 v48, v8
	v_mov_b32_e32 v49, v8
	v_mov_b32_e32 v50, v8
	v_mov_b32_e32 v51, v8
	v_mov_b32_e32 v52, v8
	v_mov_b32_e32 v53, v8
	v_mov_b32_e32 v18, v8
	v_mov_b32_e32 v19, v8
	v_mov_b32_e32 v20, v8
	v_mov_b32_e32 v21, v8
	v_mov_b32_e32 v22, v8
	v_mov_b32_e32 v23, v8
	v_mov_b32_e32 v24, v8
	v_mov_b32_e32 v25, v8
	v_mov_b32_e32 v38, v8
	v_mov_b32_e32 v39, v8
	v_mov_b32_e32 v40, v8
	v_mov_b32_e32 v41, v8
	v_mov_b32_e32 v42, v8
	v_mov_b32_e32 v43, v8
	v_mov_b32_e32 v44, v8
	v_mov_b32_e32 v45, v8
	v_mov_b32_e32 v54, v8
	v_mov_b32_e32 v55, v8
	v_mov_b32_e32 v56, v8
	v_mov_b32_e32 v57, v8
	v_mov_b32_e32 v58, v8
	v_mov_b32_e32 v59, v8
	v_mov_b32_e32 v60, v8
	v_mov_b32_e32 v61, v8
	v_mov_b32_e32 v70, v8
	v_mov_b32_e32 v71, v8
	v_mov_b32_e32 v72, v8
	v_mov_b32_e32 v73, v8
	v_mov_b32_e32 v74, v8
	v_mov_b32_e32 v75, v8
	v_mov_b32_e32 v76, v8
	v_mov_b32_e32 v77, v8
	v_mov_b32_e32 v62, v8
	v_mov_b32_e32 v63, v8
	v_mov_b32_e32 v64, v8
	v_mov_b32_e32 v65, v8
	v_mov_b32_e32 v66, v8
	v_mov_b32_e32 v67, v8
	v_mov_b32_e32 v68, v8
	v_mov_b32_e32 v69, v8
	v_mov_b32_e32 v78, v8
	v_mov_b32_e32 v79, v8
	v_mov_b32_e32 v80, v8
	v_mov_b32_e32 v81, v8
	v_mov_b32_e32 v82, v8
	v_mov_b32_e32 v83, v8
	v_mov_b32_e32 v84, v8
	v_mov_b32_e32 v85, v8
	v_mov_b32_e32 v94, v8
	v_mov_b32_e32 v95, v8
	v_mov_b32_e32 v96, v8
	v_mov_b32_e32 v97, v8
	v_mov_b32_e32 v98, v8
	v_mov_b32_e32 v99, v8
	v_mov_b32_e32 v100, v8
	v_mov_b32_e32 v101, v8
	v_mov_b32_e32 v110, v8
	v_mov_b32_e32 v111, v8
	v_mov_b32_e32 v112, v8
	v_mov_b32_e32 v113, v8
	v_mov_b32_e32 v114, v8
	v_mov_b32_e32 v115, v8
	v_mov_b32_e32 v116, v8
	v_mov_b32_e32 v117, v8
	v_mov_b32_e32 v86, v8
	v_mov_b32_e32 v87, v8
	v_mov_b32_e32 v88, v8
	v_mov_b32_e32 v89, v8
	v_mov_b32_e32 v90, v8
	v_mov_b32_e32 v91, v8
	v_mov_b32_e32 v92, v8
	v_mov_b32_e32 v93, v8
	v_mov_b32_e32 v102, v8
	v_mov_b32_e32 v103, v8
	v_mov_b32_e32 v104, v8
	v_mov_b32_e32 v105, v8
	v_mov_b32_e32 v106, v8
	v_mov_b32_e32 v107, v8
	v_mov_b32_e32 v108, v8
	v_mov_b32_e32 v109, v8
	v_mov_b32_e32 v118, v8
	v_mov_b32_e32 v119, v8
	v_mov_b32_e32 v120, v8
	v_mov_b32_e32 v121, v8
	v_mov_b32_e32 v122, v8
	v_mov_b32_e32 v123, v8
	v_mov_b32_e32 v124, v8
	v_mov_b32_e32 v125, v8
	v_mov_b32_e32 v134, v8
	v_mov_b32_e32 v135, v8
	v_mov_b32_e32 v136, v8
	v_mov_b32_e32 v137, v8
	v_mov_b32_e32 v138, v8
	v_mov_b32_e32 v139, v8
	v_mov_b32_e32 v140, v8
	v_mov_b32_e32 v141, v8
	v_readfirstlane_b32 vcc_lo, v252
	s_nop 0
	s_cmpk_ge_u32 vcc_lo, 0x100
	s_cbranch_scc0 .Lsprio3
	s_setprio 1
.Lsprio3:
.LBB0_878:
	s_add_u32 s20, s8, 0xfff80080
	s_addc_u32 s21, s9, -1
	s_add_i32 s53, 0, 0x10000
	s_cmp_eq_u32 s52, 28
	s_cselect_b32 s23, s7, s21
	s_cselect_b32 s22, s25, s20
	v_add_u32_e32 v6, s53, v170
	s_cselect_b32 s21, s5, s51
	s_cselect_b32 s20, s47, s50
	s_add_i32 s54, 0, 0x14000
	ds_read_b128 v[126:129], v6
	ds_read_b128 v[130:133], v6 offset:1024
	ds_read_b128 v[142:145], v6 offset:2048
	ds_read_b128 v[146:149], v6 offset:3072
	v_add_u32_e32 v6, s54, v170
	ds_read_b128 v[164:167], v6
	ds_read_b128 v[204:207], v6 offset:1024
	ds_read_b128 v[208:211], v6 offset:2048
	ds_read_b128 v[216:219], v6 offset:3072
	v_lshl_add_u64 v[6:7], s[8:9], 0, v[160:161]
	s_add_i32 m0, s38, 0xc000
	ds_read_b128 v[220:223], v196
	ds_read_b128 v[224:227], v196 offset:1024
	ds_read_b128 v[228:231], v196 offset:2048
	ds_read_b128 v[232:235], v196 offset:3072
	ds_read_b128 v[236:239], v196 offset:4096
	ds_read_b128 v[240:243], v196 offset:5120
	ds_read_b128 v[244:247], v196 offset:6144
	ds_read_b128 v[248:251], v196 offset:7168
	global_load_lds_dwordx4 v[6:7], off
	v_lshl_add_u64 v[6:7], s[8:9], 0, v[162:163]
	s_add_i32 m0, s38, 0xe000
	s_nop 0
	global_load_lds_dwordx4 v[6:7], off
	s_waitcnt vmcnt(8)
	s_waitcnt lgkmcnt(0)
	s_barrier
	v_mfma_f32_16x16x32_bf16 v[138:141], v[126:129], v[220:223], v[138:141]
	v_mfma_f32_16x16x32_bf16 v[134:137], v[142:145], v[220:223], v[134:137]
	v_mfma_f32_16x16x32_bf16 v[122:125], v[126:129], v[228:231], v[122:125]
	v_mfma_f32_16x16x32_bf16 v[118:121], v[142:145], v[228:231], v[118:121]
	v_mfma_f32_16x16x32_bf16 v[106:109], v[126:129], v[236:239], v[106:109]
	v_mfma_f32_16x16x32_bf16 v[102:105], v[142:145], v[236:239], v[102:105]
	v_mfma_f32_16x16x32_bf16 v[90:93], v[126:129], v[244:247], v[90:93]
	v_mfma_f32_16x16x32_bf16 v[86:89], v[142:145], v[244:247], v[86:89]
	v_mfma_f32_16x16x32_bf16 v[138:141], v[130:133], v[224:227], v[138:141]
	v_mfma_f32_16x16x32_bf16 v[134:137], v[146:149], v[224:227], v[134:137]
	v_mfma_f32_16x16x32_bf16 v[122:125], v[130:133], v[232:235], v[122:125]
	v_mfma_f32_16x16x32_bf16 v[118:121], v[146:149], v[232:235], v[118:121]
	v_mfma_f32_16x16x32_bf16 v[106:109], v[130:133], v[240:243], v[106:109]
	v_mfma_f32_16x16x32_bf16 v[102:105], v[146:149], v[240:243], v[102:105]
	v_mfma_f32_16x16x32_bf16 v[90:93], v[130:133], v[248:251], v[90:93]
	v_mfma_f32_16x16x32_bf16 v[86:89], v[146:149], v[248:251], v[86:89]
	v_mfma_f32_16x16x32_bf16 v[114:117], v[164:167], v[220:223], v[114:117]
	v_mfma_f32_16x16x32_bf16 v[110:113], v[208:211], v[220:223], v[110:113]
	v_mfma_f32_16x16x32_bf16 v[98:101], v[164:167], v[228:231], v[98:101]
	v_mfma_f32_16x16x32_bf16 v[94:97], v[208:211], v[228:231], v[94:97]
	v_mfma_f32_16x16x32_bf16 v[82:85], v[164:167], v[236:239], v[82:85]
	v_mfma_f32_16x16x32_bf16 v[78:81], v[208:211], v[236:239], v[78:81]
	v_mfma_f32_16x16x32_bf16 v[66:69], v[164:167], v[244:247], v[66:69]
	v_mfma_f32_16x16x32_bf16 v[62:65], v[208:211], v[244:247], v[62:65]
	v_mfma_f32_16x16x32_bf16 v[114:117], v[204:207], v[224:227], v[114:117]
	v_mfma_f32_16x16x32_bf16 v[110:113], v[216:219], v[224:227], v[110:113]
	v_mfma_f32_16x16x32_bf16 v[98:101], v[204:207], v[232:235], v[98:101]
	v_mfma_f32_16x16x32_bf16 v[94:97], v[216:219], v[232:235], v[94:97]
	v_mfma_f32_16x16x32_bf16 v[82:85], v[204:207], v[240:243], v[82:85]
	v_mfma_f32_16x16x32_bf16 v[78:81], v[216:219], v[240:243], v[78:81]
	v_mfma_f32_16x16x32_bf16 v[66:69], v[204:207], v[248:251], v[66:69]
	v_mfma_f32_16x16x32_bf16 v[62:65], v[216:219], v[248:251], v[62:65]
	s_barrier
	s_add_i32 s53, s53, s17
	v_lshl_add_u64 v[168:169], s[20:21], 0, v[0:1]
	s_mov_b32 m0, s53
	ds_read_b128 v[220:223], v196 offset:16384
	ds_read_b128 v[224:227], v196 offset:17408
	ds_read_b128 v[228:231], v196 offset:18432
	ds_read_b128 v[232:235], v196 offset:19456
	ds_read_b128 v[236:239], v196 offset:20480
	ds_read_b128 v[240:243], v196 offset:21504
	ds_read_b128 v[244:247], v196 offset:22528
	ds_read_b128 v[248:251], v196 offset:23552
	global_load_lds_dwordx4 v[168:169], off
	s_add_i32 m0, s53, 0x2000
	s_add_u32 s56, s20, 0x80000
	v_lshl_add_u64 v[198:199], s[20:21], 0, v[154:155]
	s_addc_u32 s57, s21, 0
	s_add_i32 s53, s54, s17
	global_load_lds_dwordx4 v[198:199], off
	v_lshl_add_u64 v[6:7], s[56:57], 0, v[0:1]
	s_mov_b32 m0, s53
	v_lshl_add_u64 v[200:201], s[22:23], 0, v[150:151]
	global_load_lds_dwordx4 v[6:7], off
	v_lshl_add_u64 v[6:7], s[56:57], 0, v[154:155]
	s_add_i32 m0, s53, 0x2000
	v_lshl_add_u64 v[202:203], s[22:23], 0, v[152:153]
	global_load_lds_dwordx4 v[6:7], off
	s_mov_b32 m0, s38
	s_nop 0
	global_load_lds_dwordx4 v[200:201], off
	s_mov_b32 m0, s39
	s_nop 0
	global_load_lds_dwordx4 v[202:203], off
	s_waitcnt vmcnt(8)
	s_waitcnt lgkmcnt(0)
	s_barrier
	v_mfma_f32_16x16x32_bf16 v[74:77], v[126:129], v[220:223], v[74:77]
	v_mfma_f32_16x16x32_bf16 v[70:73], v[142:145], v[220:223], v[70:73]
	v_mfma_f32_16x16x32_bf16 v[58:61], v[126:129], v[228:231], v[58:61]
	v_mfma_f32_16x16x32_bf16 v[54:57], v[142:145], v[228:231], v[54:57]
	v_mfma_f32_16x16x32_bf16 v[42:45], v[126:129], v[236:239], v[42:45]
	v_mfma_f32_16x16x32_bf16 v[38:41], v[142:145], v[236:239], v[38:41]
	v_mfma_f32_16x16x32_bf16 v[22:25], v[126:129], v[244:247], v[22:25]
	v_mfma_f32_16x16x32_bf16 v[18:21], v[142:145], v[244:247], v[18:21]
	v_mfma_f32_16x16x32_bf16 v[74:77], v[130:133], v[224:227], v[74:77]
	v_mfma_f32_16x16x32_bf16 v[70:73], v[146:149], v[224:227], v[70:73]
	v_mfma_f32_16x16x32_bf16 v[58:61], v[130:133], v[232:235], v[58:61]
	v_mfma_f32_16x16x32_bf16 v[54:57], v[146:149], v[232:235], v[54:57]
	v_mfma_f32_16x16x32_bf16 v[42:45], v[130:133], v[240:243], v[42:45]
	v_mfma_f32_16x16x32_bf16 v[38:41], v[146:149], v[240:243], v[38:41]
	v_mfma_f32_16x16x32_bf16 v[22:25], v[130:133], v[248:251], v[22:25]
	v_mfma_f32_16x16x32_bf16 v[18:21], v[146:149], v[248:251], v[18:21]
	v_mfma_f32_16x16x32_bf16 v[50:53], v[164:167], v[220:223], v[50:53]
	v_mfma_f32_16x16x32_bf16 v[46:49], v[208:211], v[220:223], v[46:49]
	v_mfma_f32_16x16x32_bf16 v[34:37], v[164:167], v[228:231], v[34:37]
	v_mfma_f32_16x16x32_bf16 v[30:33], v[208:211], v[228:231], v[30:33]
	v_mfma_f32_16x16x32_bf16 v[26:29], v[164:167], v[236:239], v[26:29]
	v_mfma_f32_16x16x32_bf16 v[2:5], v[208:211], v[236:239], v[2:5]
	v_mfma_f32_16x16x32_bf16 v[12:15], v[164:167], v[244:247], v[12:15]
	v_mfma_f32_16x16x32_bf16 v[6:9], v[208:211], v[244:247], v[8:11]
	v_mfma_f32_16x16x32_bf16 v[50:53], v[204:207], v[224:227], v[50:53]
	v_mfma_f32_16x16x32_bf16 v[46:49], v[216:219], v[224:227], v[46:49]
	v_mfma_f32_16x16x32_bf16 v[34:37], v[204:207], v[232:235], v[34:37]
	v_mfma_f32_16x16x32_bf16 v[30:33], v[216:219], v[232:235], v[30:33]
	v_mfma_f32_16x16x32_bf16 v[26:29], v[204:207], v[240:243], v[26:29]
	v_mfma_f32_16x16x32_bf16 v[2:5], v[216:219], v[240:243], v[2:5]
	v_mfma_f32_16x16x32_bf16 v[12:15], v[204:207], v[248:251], v[12:15]
	v_mfma_f32_16x16x32_bf16 v[6:9], v[216:219], v[248:251], v[6:9]
	s_barrier
	s_add_i32 s53, 0, 0x18000
	v_add_u32_e32 v10, s53, v170
	s_add_i32 s54, 0, 0x1c000
	ds_read_b128 v[126:129], v10
	ds_read_b128 v[130:133], v10 offset:1024
	ds_read_b128 v[142:145], v10 offset:2048
	ds_read_b128 v[146:149], v10 offset:3072
	v_add_u32_e32 v10, s54, v170
	ds_read_b128 v[164:167], v10
	ds_read_b128 v[204:207], v10 offset:1024
	ds_read_b128 v[208:211], v10 offset:2048
	ds_read_b128 v[216:219], v10 offset:3072
	s_add_u32 s22, s22, 0x80000
	s_addc_u32 s23, s23, 0
	s_mov_b32 m0, s40
	v_lshl_add_u64 v[10:11], s[22:23], 0, v[150:151]
	ds_read_b128 v[220:223], v196 offset:32768
	ds_read_b128 v[224:227], v196 offset:33792
	ds_read_b128 v[228:231], v196 offset:34816
	ds_read_b128 v[232:235], v196 offset:35840
	ds_read_b128 v[236:239], v196 offset:36864
	ds_read_b128 v[240:243], v196 offset:37888
	ds_read_b128 v[244:247], v196 offset:38912
	ds_read_b128 v[248:251], v196 offset:39936
	global_load_lds_dwordx4 v[10:11], off
	v_lshl_add_u64 v[10:11], s[22:23], 0, v[152:153]
	s_mov_b32 m0, s41
	s_nop 0
	global_load_lds_dwordx4 v[10:11], off
	s_waitcnt vmcnt(8)
	s_waitcnt lgkmcnt(0)
	s_barrier
	v_mfma_f32_16x16x32_bf16 v[138:141], v[126:129], v[220:223], v[138:141]
	v_mfma_f32_16x16x32_bf16 v[134:137], v[142:145], v[220:223], v[134:137]
	v_mfma_f32_16x16x32_bf16 v[122:125], v[126:129], v[228:231], v[122:125]
	v_mfma_f32_16x16x32_bf16 v[118:121], v[142:145], v[228:231], v[118:121]
	v_mfma_f32_16x16x32_bf16 v[106:109], v[126:129], v[236:239], v[106:109]
	v_mfma_f32_16x16x32_bf16 v[102:105], v[142:145], v[236:239], v[102:105]
	v_mfma_f32_16x16x32_bf16 v[90:93], v[126:129], v[244:247], v[90:93]
	v_mfma_f32_16x16x32_bf16 v[86:89], v[142:145], v[244:247], v[86:89]
	v_mfma_f32_16x16x32_bf16 v[138:141], v[130:133], v[224:227], v[138:141]
	v_mfma_f32_16x16x32_bf16 v[134:137], v[146:149], v[224:227], v[134:137]
	v_mfma_f32_16x16x32_bf16 v[122:125], v[130:133], v[232:235], v[122:125]
	v_mfma_f32_16x16x32_bf16 v[118:121], v[146:149], v[232:235], v[118:121]
	v_mfma_f32_16x16x32_bf16 v[106:109], v[130:133], v[240:243], v[106:109]
	v_mfma_f32_16x16x32_bf16 v[102:105], v[146:149], v[240:243], v[102:105]
	v_mfma_f32_16x16x32_bf16 v[90:93], v[130:133], v[248:251], v[90:93]
	v_mfma_f32_16x16x32_bf16 v[86:89], v[146:149], v[248:251], v[86:89]
	v_mfma_f32_16x16x32_bf16 v[114:117], v[164:167], v[220:223], v[114:117]
	v_mfma_f32_16x16x32_bf16 v[110:113], v[208:211], v[220:223], v[110:113]
	v_mfma_f32_16x16x32_bf16 v[98:101], v[164:167], v[228:231], v[98:101]
	v_mfma_f32_16x16x32_bf16 v[94:97], v[208:211], v[228:231], v[94:97]
	v_mfma_f32_16x16x32_bf16 v[82:85], v[164:167], v[236:239], v[82:85]
	v_mfma_f32_16x16x32_bf16 v[78:81], v[208:211], v[236:239], v[78:81]
	v_mfma_f32_16x16x32_bf16 v[66:69], v[164:167], v[244:247], v[66:69]
	v_mfma_f32_16x16x32_bf16 v[62:65], v[208:211], v[244:247], v[62:65]
	v_mfma_f32_16x16x32_bf16 v[114:117], v[204:207], v[224:227], v[114:117]
	v_mfma_f32_16x16x32_bf16 v[110:113], v[216:219], v[224:227], v[110:113]
	v_mfma_f32_16x16x32_bf16 v[98:101], v[204:207], v[232:235], v[98:101]
	v_mfma_f32_16x16x32_bf16 v[94:97], v[216:219], v[232:235], v[94:97]
	v_mfma_f32_16x16x32_bf16 v[82:85], v[204:207], v[240:243], v[82:85]
	v_mfma_f32_16x16x32_bf16 v[78:81], v[216:219], v[240:243], v[78:81]
	v_mfma_f32_16x16x32_bf16 v[66:69], v[204:207], v[248:251], v[66:69]
	v_mfma_f32_16x16x32_bf16 v[62:65], v[216:219], v[248:251], v[62:65]
	s_barrier
	s_add_i32 s22, s53, s17
	v_lshl_add_u64 v[10:11], v[168:169], 0, s[36:37]
	s_mov_b32 m0, s22
	ds_read_b128 v[220:223], v196 offset:49152
	ds_read_b128 v[224:227], v196 offset:50176
	ds_read_b128 v[228:231], v196 offset:51200
	ds_read_b128 v[232:235], v196 offset:52224
	ds_read_b128 v[236:239], v196 offset:53248
	ds_read_b128 v[240:243], v196 offset:54272
	ds_read_b128 v[244:247], v196 offset:55296
	ds_read_b128 v[248:251], v196 offset:56320
	global_load_lds_dwordx4 v[10:11], off
	s_add_i32 m0, s22, 0x2000
	s_add_u32 s20, s20, 0x80080
	v_lshl_add_u64 v[10:11], v[198:199], 0, s[36:37]
	s_addc_u32 s21, s21, 0
	s_add_i32 s22, s54, s17
	global_load_lds_dwordx4 v[10:11], off
	v_lshl_add_u64 v[10:11], s[20:21], 0, v[0:1]
	s_mov_b32 m0, s22
	s_nop 0
	global_load_lds_dwordx4 v[10:11], off
	v_lshl_add_u64 v[10:11], s[20:21], 0, v[154:155]
	s_add_i32 m0, s22, 0x2000
	s_nop 0
	global_load_lds_dwordx4 v[10:11], off
	v_lshl_add_u64 v[10:11], v[200:201], 0, s[36:37]
	s_mov_b32 m0, s2
	s_nop 0
	global_load_lds_dwordx4 v[10:11], off
	v_lshl_add_u64 v[10:11], v[202:203], 0, s[36:37]
	s_mov_b32 m0, s3
	s_nop 0
	global_load_lds_dwordx4 v[10:11], off
	s_waitcnt vmcnt(8)
	s_waitcnt lgkmcnt(0)
	s_barrier
	v_mfma_f32_16x16x32_bf16 v[74:77], v[126:129], v[220:223], v[74:77]
	v_mfma_f32_16x16x32_bf16 v[70:73], v[142:145], v[220:223], v[70:73]
	v_mfma_f32_16x16x32_bf16 v[58:61], v[126:129], v[228:231], v[58:61]
	v_mfma_f32_16x16x32_bf16 v[54:57], v[142:145], v[228:231], v[54:57]
	v_mfma_f32_16x16x32_bf16 v[42:45], v[126:129], v[236:239], v[42:45]
	v_mfma_f32_16x16x32_bf16 v[38:41], v[142:145], v[236:239], v[38:41]
	v_mfma_f32_16x16x32_bf16 v[22:25], v[126:129], v[244:247], v[22:25]
	v_mfma_f32_16x16x32_bf16 v[18:21], v[142:145], v[244:247], v[18:21]
	v_mfma_f32_16x16x32_bf16 v[74:77], v[130:133], v[224:227], v[74:77]
	v_mfma_f32_16x16x32_bf16 v[70:73], v[146:149], v[224:227], v[70:73]
	v_mfma_f32_16x16x32_bf16 v[58:61], v[130:133], v[232:235], v[58:61]
	v_mfma_f32_16x16x32_bf16 v[54:57], v[146:149], v[232:235], v[54:57]
	v_mfma_f32_16x16x32_bf16 v[42:45], v[130:133], v[240:243], v[42:45]
	v_mfma_f32_16x16x32_bf16 v[38:41], v[146:149], v[240:243], v[38:41]
	v_mfma_f32_16x16x32_bf16 v[22:25], v[130:133], v[248:251], v[22:25]
	v_mfma_f32_16x16x32_bf16 v[18:21], v[146:149], v[248:251], v[18:21]
	v_mfma_f32_16x16x32_bf16 v[50:53], v[164:167], v[220:223], v[50:53]
	v_mfma_f32_16x16x32_bf16 v[46:49], v[208:211], v[220:223], v[46:49]
	v_mfma_f32_16x16x32_bf16 v[34:37], v[164:167], v[228:231], v[34:37]
	v_mfma_f32_16x16x32_bf16 v[30:33], v[208:211], v[228:231], v[30:33]
	v_mfma_f32_16x16x32_bf16 v[26:29], v[164:167], v[236:239], v[26:29]
	v_mfma_f32_16x16x32_bf16 v[2:5], v[208:211], v[236:239], v[2:5]
	v_mfma_f32_16x16x32_bf16 v[10:13], v[164:167], v[244:247], v[12:15]
	v_mfma_f32_16x16x32_bf16 v[6:9], v[208:211], v[244:247], v[6:9]
	v_mfma_f32_16x16x32_bf16 v[50:53], v[204:207], v[224:227], v[50:53]
	v_mfma_f32_16x16x32_bf16 v[46:49], v[216:219], v[224:227], v[46:49]
	v_mfma_f32_16x16x32_bf16 v[34:37], v[204:207], v[232:235], v[34:37]
	v_mfma_f32_16x16x32_bf16 v[30:33], v[216:219], v[232:235], v[30:33]
	v_mfma_f32_16x16x32_bf16 v[26:29], v[204:207], v[240:243], v[26:29]
	v_mfma_f32_16x16x32_bf16 v[2:5], v[216:219], v[240:243], v[2:5]
	v_mfma_f32_16x16x32_bf16 v[12:15], v[204:207], v[248:251], v[10:13]
	v_mfma_f32_16x16x32_bf16 v[8:11], v[216:219], v[248:251], v[6:9]
	s_barrier
	s_add_i32 s52, s52, 2
	s_add_u32 s8, s8, 0x100
	s_addc_u32 s9, s9, 0
	s_add_u32 s50, s50, 0x100
	s_addc_u32 s51, s51, 0
	s_cmp_gt_u32 s52, 29
	s_cbranch_scc0 .LBB0_878
	s_setprio 0
	s_and_b64 vcc, exec, s[74:75]
	s_cbranch_vccz .LBB0_881
	s_barrier
